# ret_kv and ret_out: remaining bf16 RNE bit-trick sites feeding d16_hi LDS stores replaced by v_cvt_pk_bf16_f32 (74 sites)
# baseline (speedup 1.0000x reference)
.LBB0_193:
	v_mul_f32_e32 v0, 0xbfb8aa3b, v65
	v_rndne_f32_e32 v1, v0
	v_sub_f32_e32 v2, v0, v1
	v_fma_f32 v0, v65, s70, -v0
	v_fmac_f32_e32 v0, 0xb2a5705f, v65
	v_add_f32_e32 v0, v2, v0
	v_cvt_i32_f32_e32 v1, v1
	v_exp_f32_e32 v0, v0
	v_cmp_nlt_f32_e32 vcc, s71, v65
	s_ashr_i32 s39, s38, 31
	s_lshl_b64 s[26:27], s[38:39], 14
	v_ldexp_f32 v0, v0, v1
	v_cndmask_b32_e32 v0, 0, v0, vcc
	v_cmp_ngt_f32_e32 vcc, s3, v65
	s_add_u32 s26, s58, s26
	v_ashrrev_i32_e32 v86, 3, v100
	v_cndmask_b32_e32 v2, v238, v0, vcc
	v_add_f32_e32 v3, 1.0, v2
	v_add_f32_e32 v0, -1.0, v3
	v_sub_f32_e32 v1, v0, v3
	v_add_f32_e32 v1, 1.0, v1
	v_sub_f32_e32 v0, v2, v0
	v_add_f32_e32 v4, v0, v1
	v_frexp_mant_f32_e32 v0, v3
	v_cmp_gt_f32_e32 vcc, s5, v0
	v_cvt_f64_f32_e32 v[0:1], v3
	v_frexp_exp_i32_f64_e32 v0, v[0:1]
	v_subbrev_co_u32_e32 v0, vcc, 0, v0, vcc
	v_sub_u32_e32 v1, 0, v0
	v_ldexp_f32 v3, v3, v1
	v_ldexp_f32 v1, v4, v1
	v_add_f32_e32 v4, -1.0, v3
	v_add_f32_e32 v7, 1.0, v3
	v_add_f32_e32 v5, 1.0, v4
	v_add_f32_e32 v15, -1.0, v7
	v_sub_f32_e32 v5, v3, v5
	v_sub_f32_e32 v3, v3, v15
	v_add_f32_e32 v5, v1, v5
	v_add_f32_e32 v1, v1, v3
	v_add_f32_e32 v3, v7, v1
	v_rcp_f32_e32 v15, v3
	v_add_f32_e32 v6, v4, v5
	v_sub_f32_e32 v4, v4, v6
	v_add_f32_e32 v4, v5, v4
	v_sub_f32_e32 v5, v7, v3
	v_add_f32_e32 v1, v1, v5
	v_mul_f32_e32 v5, v6, v15
	v_mul_f32_e32 v7, v3, v5
	v_fma_f32 v17, v5, v3, -v7
	v_fmac_f32_e32 v17, v5, v1
	v_add_f32_e32 v18, v7, v17
	v_sub_f32_e32 v19, v6, v18
	v_sub_f32_e32 v6, v6, v19
	v_sub_f32_e32 v7, v18, v7
	v_sub_f32_e32 v6, v6, v18
	v_add_f32_e32 v4, v4, v6
	v_sub_f32_e32 v6, v7, v17
	v_add_f32_e32 v4, v6, v4
	v_add_f32_e32 v6, v19, v4
	v_mul_f32_e32 v7, v15, v6
	v_mul_f32_e32 v17, v3, v7
	v_fma_f32 v3, v7, v3, -v17
	v_fmac_f32_e32 v3, v7, v1
	v_sub_f32_e32 v1, v19, v6
	v_add_f32_e32 v1, v4, v1
	v_add_f32_e32 v4, v17, v3
	v_sub_f32_e32 v18, v6, v4
	v_sub_f32_e32 v6, v6, v18
	v_sub_f32_e32 v17, v4, v17
	v_sub_f32_e32 v4, v6, v4
	v_add_f32_e32 v1, v1, v4
	v_sub_f32_e32 v3, v17, v3
	v_cvt_f32_i32_e32 v0, v0
	v_add_f32_e32 v1, v3, v1
	v_add_f32_e32 v3, v5, v7
	v_add_f32_e32 v1, v18, v1
	v_sub_f32_e32 v4, v3, v5
	v_mul_f32_e32 v1, v15, v1
	v_sub_f32_e32 v4, v7, v4
	v_add_f32_e32 v1, v4, v1
	v_mul_f32_e32 v7, 0x3f317218, v0
	v_add_f32_e32 v4, v3, v1
	v_fma_f32 v15, v0, s6, -v7
	v_mul_f32_e32 v5, v4, v4
	v_fmac_f32_e32 v15, 0xb102e308, v0
	v_sub_f32_e32 v0, v4, v3
	v_fmamk_f32 v6, v5, 0x3e9b6dac, v222
	v_sub_f32_e32 v0, v1, v0
	v_add_f32_e32 v1, v7, v15
	v_fmaak_f32 v6, v5, v6, 0x3f2aaada
	v_sub_f32_e32 v3, v1, v7
	v_ldexp_f32 v7, v4, 1
	v_mul_f32_e32 v4, v4, v5
	v_mul_f32_e32 v4, v4, v6
	v_add_f32_e32 v5, v7, v4
	v_sub_f32_e32 v6, v5, v7
	v_ldexp_f32 v0, v0, 1
	v_sub_f32_e32 v4, v4, v6
	v_add_f32_e32 v0, v0, v4
	v_add_f32_e32 v4, v5, v0
	v_sub_f32_e32 v5, v4, v5
	v_sub_f32_e32 v0, v0, v5
	v_add_f32_e32 v5, v1, v4
	v_sub_f32_e32 v6, v5, v1
	v_sub_f32_e32 v7, v5, v6
	v_sub_f32_e32 v3, v15, v3
	v_sub_f32_e32 v1, v1, v7
	v_sub_f32_e32 v4, v4, v6
	v_add_f32_e32 v1, v4, v1
	v_add_f32_e32 v4, v3, v0
	v_sub_f32_e32 v6, v4, v3
	v_sub_f32_e32 v7, v4, v6
	v_sub_f32_e32 v3, v3, v7
	v_sub_f32_e32 v0, v0, v6
	v_add_f32_e32 v1, v4, v1
	v_add_f32_e32 v0, v0, v3
	v_add_f32_e32 v3, v5, v1
	v_sub_f32_e32 v4, v3, v5
	v_sub_f32_e32 v1, v1, v4
	v_add_f32_e32 v0, v0, v1
	v_mul_f32_e32 v1, 0xbfb8aa3b, v63
	v_add_f32_e32 v0, v3, v0
	v_rndne_f32_e32 v3, v1
	v_sub_f32_e32 v4, v1, v3
	v_fma_f32 v1, v63, s70, -v1
	v_fmac_f32_e32 v1, 0xb2a5705f, v63
	v_add_f32_e32 v1, v4, v1
	v_exp_f32_e32 v1, v1
	v_cvt_i32_f32_e32 v3, v3
	v_cmp_neq_f32_e32 vcc, s21, v2
	s_addc_u32 s27, s59, s27
	v_ashrrev_i32_e32 v87, 31, v86
	v_cndmask_b32_e32 v0, v238, v0, vcc
	v_cmp_lt_f32_e64 vcc, |v2|, s7
	v_cvt_pk_bf16_f32 v82, v48, v49
	v_cvt_pk_bf16_f32 v83, v46, v47
	v_cvt_pk_bf16_f32 v84, v44, v45
	v_cvt_pk_bf16_f32 v85, v42, v43
	v_cvt_pk_bf16_f32 v40, v40, v41
	s_nop 1
	v_cndmask_b32_e32 v99, v0, v2, vcc
	v_ldexp_f32 v0, v1, v3
	v_cmp_nlt_f32_e32 vcc, s71, v63
	v_cvt_pk_bf16_f32 v41, v38, v39
	v_cvt_pk_bf16_f32 v42, v36, v37
	v_cvt_pk_bf16_f32 v43, v34, v31
	v_and_b32_e32 v101, 15, v100
	v_and_b32_e32 v107, 48, v100
	v_cndmask_b32_e32 v0, 0, v0, vcc
	v_cmp_ngt_f32_e32 vcc, s3, v63
	v_add_u32_e32 v98, s2, v107
	v_or_b32_e32 v116, 64, v101
	v_cndmask_b32_e32 v0, v238, v0, vcc
	v_add_f32_e32 v4, 1.0, v0
	v_add_f32_e32 v1, -1.0, v4
	v_sub_f32_e32 v2, v1, v4
	v_add_f32_e32 v2, 1.0, v2
	v_sub_f32_e32 v1, v0, v1
	v_add_f32_e32 v5, v1, v2
	v_frexp_mant_f32_e32 v1, v4
	v_cvt_f64_f32_e32 v[2:3], v4
	v_cmp_gt_f32_e32 vcc, s5, v1
	v_frexp_exp_i32_f64_e32 v1, v[2:3]
	s_lshl_b32 s88, s22, 1
	v_subbrev_co_u32_e32 v1, vcc, 0, v1, vcc
	v_sub_u32_e32 v2, 0, v1
	v_ldexp_f32 v3, v4, v2
	v_add_f32_e32 v4, -1.0, v3
	v_add_f32_e32 v6, 1.0, v3
	v_ldexp_f32 v2, v5, v2
	v_add_f32_e32 v5, 1.0, v4
	v_add_f32_e32 v7, -1.0, v6
	v_sub_f32_e32 v5, v3, v5
	v_sub_f32_e32 v3, v3, v7
	v_add_f32_e32 v5, v2, v5
	v_add_f32_e32 v2, v2, v3
	v_add_f32_e32 v17, v6, v2
	v_rcp_f32_e32 v3, v17
	v_add_f32_e32 v15, v4, v5
	v_sub_f32_e32 v4, v4, v15
	v_add_f32_e32 v18, v5, v4
	v_sub_f32_e32 v4, v6, v17
	v_add_f32_e32 v19, v2, v4
	v_mul_f32_e32 v2, v15, v3
	v_mul_f32_e32 v33, v17, v2
	v_fma_f32 v35, v2, v17, -v33
	v_fmac_f32_e32 v35, v2, v19
	v_add_f32_e32 v50, v33, v35
	v_sub_f32_e32 v54, v15, v50
	v_sub_f32_e32 v15, v15, v54
	v_sub_f32_e32 v33, v50, v33
	v_sub_f32_e32 v15, v15, v50
	v_add_f32_e32 v15, v18, v15
	v_sub_f32_e32 v18, v33, v35
	v_add_f32_e32 v15, v18, v15
	v_add_f32_e32 v33, v54, v15
	v_mul_f32_e32 v35, v3, v33
	global_load_dwordx4 v[4:7], v[12:13], off offset:1024
	global_load_dwordx4 v[50:53], v[12:13], off offset:1040
	v_mul_f32_e32 v63, v17, v35
	v_sub_f32_e32 v65, v54, v33
	global_load_dwordx4 v[54:57], v[12:13], off offset:1072
	global_load_dwordx4 v[58:61], v[12:13], off offset:1056
	v_lshlrev_b32_e32 v12, 4, v100
	v_fma_f32 v17, v35, v17, -v63
	v_and_b32_e32 v184, 0x70, v12
	v_fmac_f32_e32 v17, v35, v19
	v_lshl_add_u64 v[12:13], s[26:27], 0, v[184:185]
	v_lshlrev_b64 v[18:19], 7, v[86:87]
	v_lshl_add_u64 v[18:19], v[12:13], 0, v[18:19]
	global_load_dwordx4 v[66:69], v[18:19], off
	v_add_u32_e32 v18, 0x100, v100
	v_ashrrev_i32_e32 v88, 3, v18
	v_ashrrev_i32_e32 v89, 31, v88
	v_lshlrev_b64 v[18:19], 7, v[88:89]
	v_lshl_add_u64 v[18:19], v[12:13], 0, v[18:19]
	global_load_dwordx4 v[70:73], v[18:19], off
	v_add_u32_e32 v18, 0x200, v100
	v_ashrrev_i32_e32 v90, 3, v18
	v_ashrrev_i32_e32 v91, 31, v90
	v_lshlrev_b64 v[18:19], 7, v[90:91]
	v_lshl_add_u64 v[18:19], v[12:13], 0, v[18:19]
	global_load_dwordx4 v[74:77], v[18:19], off
	v_add_u32_e32 v18, 0x300, v100
	v_ashrrev_i32_e32 v92, 3, v18
	v_ashrrev_i32_e32 v93, 31, v92
	v_lshlrev_b64 v[18:19], 7, v[92:93]
	v_lshl_add_u64 v[12:13], v[12:13], 0, v[18:19]
	global_load_dwordx4 v[78:81], v[12:13], off
	v_cvt_pk_bf16_f32 v19, v8, v9
	v_cvt_pk_bf16_f32 v8, v10, v11
	v_add_f32_e32 v13, v63, v17
	v_cvt_pk_bf16_f32 v9, v26, v27
	v_cvt_pk_bf16_f32 v10, v28, v29
	v_cvt_pk_bf16_f32 v11, v32, v30
	ds_write_b128 v16, v[8:11] offset:18480
	v_mul_u32_u24_e32 v8, 0x1100, v62
	v_add_f32_e32 v12, v15, v65
	v_sub_f32_e32 v15, v13, v63
	v_sub_f32_e32 v63, v33, v13
	v_mul_u32_u24_e32 v9, 0x21c0, v62
	v_lshlrev_b32_e32 v10, 1, v64
	v_lshlrev_b32_e32 v8, 1, v8
	v_sub_f32_e32 v18, v33, v63
	v_add3_u32 v9, v14, v9, v10
	v_add3_u32 v8, s2, v10, v8
	v_sub_f32_e32 v13, v18, v13
	ds_write_b128 v16, v[82:85] offset:18432
	ds_write_b128 v16, v[40:43] offset:18448
	v_cvt_pk_bf16_f32 v18, v20, v21
	v_cvt_pk_bf16_f32 v20, v22, v23
	v_cvt_pk_bf16_f32 v21, v24, v25
	ds_write_b128 v16, v[18:21] offset:18464
	v_and_b32_e32 v32, 0xffffffe0, v64
	v_or_b32_e32 v105, v32, v101
	v_add_f32_e32 v33, v12, v13
	v_mad_u64_u32 v[12:13], s[26:27], v105, s4, v[98:99]
	v_sub_f32_e32 v15, v15, v17
	v_cvt_f32_i32_e32 v1, v1
	v_cmp_neq_f32_e32 vcc, s21, v0
	v_or_b32_e32 v129, 16, v101
	v_or_b32_e32 v128, 32, v101
	v_mul_f32_e32 v39, 0x3f317218, v1
	v_fma_f32 v40, v1, s6, -v39
	v_fmac_f32_e32 v40, 0xb102e308, v1
	v_or_b32_e32 v127, 48, v101
	v_or_b32_e32 v119, 0x50, v101
	v_or_b32_e32 v117, 0x60, v101
	v_or_b32_e32 v115, 0x70, v101
	s_mov_b32 s36, 0x800000
	s_waitcnt vmcnt(0)
	ds_write_b16 v9, v4 offset:36864
	ds_write_b16_d16_hi v8, v4 offset:37136
	ds_write_b16 v9, v5 offset:37408
	ds_write_b16_d16_hi v9, v5 offset:37680
	ds_write_b16 v9, v6 offset:37952
	ds_write_b16_d16_hi v9, v6 offset:38224
	ds_write_b16 v9, v7 offset:38496
	ds_write_b16_d16_hi v9, v7 offset:38768
	ds_write_b16 v9, v50 offset:39040
	ds_write_b16_d16_hi v9, v50 offset:39312
	ds_write_b16 v9, v51 offset:39584
	ds_write_b16_d16_hi v9, v51 offset:39856
	ds_write_b16 v9, v52 offset:40128
	ds_write_b16_d16_hi v9, v52 offset:40400
	ds_write_b16 v9, v53 offset:40672
	ds_write_b16_d16_hi v9, v53 offset:40944
	ds_write_b16 v9, v58 offset:41216
	ds_write_b16_d16_hi v9, v58 offset:41488
	ds_write_b16 v9, v59 offset:41760
	ds_write_b16_d16_hi v9, v59 offset:42032
	ds_write_b16 v9, v60 offset:42304
	ds_write_b16_d16_hi v9, v60 offset:42576
	ds_write_b16 v9, v61 offset:42848
	ds_write_b16_d16_hi v9, v61 offset:43120
	ds_write_b16 v9, v54 offset:43392
	ds_write_b16_d16_hi v9, v54 offset:43664
	ds_write_b16 v9, v55 offset:43936
	ds_write_b16_d16_hi v9, v55 offset:44208
	ds_write_b16 v9, v56 offset:44480
	ds_write_b16_d16_hi v9, v56 offset:44752
	ds_write_b16 v9, v57 offset:45024
	ds_write_b16_d16_hi v9, v57 offset:45296
	v_add_u32_e32 v4, s2, v184
	v_mad_u64_u32 v[6:7], s[26:27], v86, s4, v[4:5]
	v_add_f32_e32 v8, v15, v33
	v_add_f32_e32 v8, v63, v8
	v_mul_f32_e32 v3, v3, v8
	v_add_f32_e32 v33, v2, v35
	ds_write_b128 v6, v[66:69] offset:54272
	v_mad_u64_u32 v[6:7], s[26:27], v88, s4, v[4:5]
	v_sub_f32_e32 v2, v33, v2
	v_sub_f32_e32 v2, v35, v2
	v_add_f32_e32 v35, v2, v3
	ds_write_b128 v6, v[70:73] offset:54272
	v_mad_u64_u32 v[6:7], s[26:27], v90, s4, v[4:5]
	v_mad_u64_u32 v[4:5], s[26:27], v92, s4, v[4:5]
	v_add_f32_e32 v36, v33, v35
	ds_write_b128 v6, v[74:77] offset:54272
	v_mul_f32_e32 v37, v36, v36
	v_fmamk_f32 v2, v37, 0x3e9b6dac, v222
	v_fmaak_f32 v38, v37, v2, 0x3f2aaada
	v_sub_f32_e32 v1, v36, v33
	v_add_f32_e32 v33, v39, v40
	ds_write_b128 v4, v[78:81] offset:54272
	v_mul_u32_u24_e32 v4, 0x48, v101
	v_lshlrev_b32_e32 v110, 1, v4
	v_add_u32_e32 v34, v98, v110
	s_waitcnt lgkmcnt(0)
	s_barrier
	ds_read_b128 v[24:27], v12
	ds_read_b128 v[28:31], v12 offset:2304
	ds_read_b128 v[4:7], v34 offset:18432
	ds_read_b128 v[20:23], v12 offset:64
	ds_read_b128 v[16:19], v12 offset:2368
	ds_read_b128 v[12:15], v34 offset:18496
	s_waitcnt lgkmcnt(3)
	v_mfma_f32_16x16x32_bf16 v[8:11], v[24:27], v[4:7], 0
	v_sub_f32_e32 v1, v35, v1
	v_ldexp_f32 v1, v1, 1
	v_add3_u32 v107, s2, v110, v107
	v_mfma_f32_16x16x32_bf16 v[4:7], v[28:31], v[4:7], 0
	v_add_u32_e32 v110, 0x1b00, v107
	s_waitcnt lgkmcnt(0)
	v_mfma_f32_16x16x32_bf16 v[92:95], v[20:23], v[12:15], v[8:11]
	s_nop 2
	ds_read_b128 v[8:11], v34 offset:20736
	v_mfma_f32_16x16x32_bf16 v[60:63], v[16:19], v[12:15], v[4:7]
	ds_read_b128 v[12:15], v34 offset:20800
	s_waitcnt lgkmcnt(1)
	v_mfma_f32_16x16x32_bf16 v[2:5], v[24:27], v[8:11], 0
	v_mfma_f32_16x16x32_bf16 v[6:9], v[28:31], v[8:11], 0
	v_sub_f32_e32 v10, v33, v39
	s_waitcnt lgkmcnt(0)
	v_mfma_f32_16x16x32_bf16 v[88:91], v[20:23], v[12:15], v[2:5]
	s_nop 3
	ds_read_b128 v[2:5], v34 offset:23040
	v_mfma_f32_16x16x32_bf16 v[56:59], v[16:19], v[12:15], v[6:9]
	v_sub_f32_e32 v14, v40, v10
	v_mul_f32_e32 v10, v36, v37
	v_mul_f32_e32 v35, v10, v38
	ds_read_b128 v[10:13], v34 offset:23104
	s_waitcnt lgkmcnt(1)
	v_mfma_f32_16x16x32_bf16 v[6:9], v[24:27], v[2:5], 0
	v_ldexp_f32 v15, v36, 1
	v_add_f32_e32 v36, v15, v35
	v_sub_f32_e32 v15, v36, v15
	v_mfma_f32_16x16x32_bf16 v[2:5], v[28:31], v[2:5], 0
	v_sub_f32_e32 v15, v35, v15
	v_add_f32_e32 v1, v1, v15
	v_add_f32_e32 v15, v36, v1
	s_waitcnt lgkmcnt(0)
	v_mfma_f32_16x16x32_bf16 v[84:87], v[20:23], v[10:13], v[6:9]
	v_add_f32_e32 v35, v33, v15
	s_nop 1
	ds_read_b128 v[6:9], v34 offset:25344
	v_mfma_f32_16x16x32_bf16 v[52:55], v[16:19], v[10:13], v[2:5]
	ds_read_b128 v[10:13], v34 offset:25408
	s_nop 1
	v_sub_f32_e32 v2, v15, v36
	v_sub_f32_e32 v1, v1, v2
	s_waitcnt lgkmcnt(1)
	v_mfma_f32_16x16x32_bf16 v[2:5], v[24:27], v[6:9], 0
	v_sub_f32_e32 v36, v35, v33
	v_sub_f32_e32 v37, v35, v36
	v_sub_f32_e32 v33, v33, v37
	v_mfma_f32_16x16x32_bf16 v[6:9], v[28:31], v[6:9], 0
	v_sub_f32_e32 v15, v15, v36
	v_add_f32_e32 v15, v15, v33
	v_mad_u32_u24 v33, v116, s4, v98
	s_waitcnt lgkmcnt(0)
	v_mfma_f32_16x16x32_bf16 v[80:83], v[20:23], v[10:13], v[2:5]
	v_add_f32_e32 v34, v14, v1
	v_lshlrev_b32_e32 v36, 5, v100
	v_and_b32_e32 v104, 32, v36
	ds_read_b128 v[2:5], v33 offset:18432
	v_mfma_f32_16x16x32_bf16 v[48:51], v[16:19], v[10:13], v[6:9]
	v_sub_f32_e32 v10, v34, v14
	v_sub_f32_e32 v11, v34, v10
	v_sub_f32_e32 v14, v14, v11
	v_sub_f32_e32 v1, v1, v10
	ds_read_b128 v[10:13], v33 offset:18496
	s_waitcnt lgkmcnt(1)
	v_mfma_f32_16x16x32_bf16 v[6:9], v[24:27], v[2:5], 0
	v_add_f32_e32 v1, v1, v14
	v_add_f32_e32 v14, v34, v15
	v_add_f32_e32 v15, v35, v14
	s_waitcnt lgkmcnt(0)
	v_mfma_f32_16x16x32_bf16 v[76:79], v[20:23], v[10:13], v[6:9]
	v_lshlrev_b32_e32 v184, 1, v104
	s_movk_i32 s4, 0x110
	s_nop 0
	v_sub_f32_e32 v6, v15, v35
	v_mfma_f32_16x16x32_bf16 v[2:5], v[28:31], v[2:5], 0
	v_sub_f32_e32 v14, v14, v6
	ds_read_b128 v[6:9], v33 offset:20736
	v_add_f32_e32 v1, v1, v14
	v_mfma_f32_16x16x32_bf16 v[44:47], v[16:19], v[10:13], v[2:5]
	ds_read_b128 v[10:13], v33 offset:20800
	v_add_f32_e32 v1, v15, v1
	v_cndmask_b32_e32 v1, v238, v1, vcc
	s_waitcnt lgkmcnt(1)
	v_mfma_f32_16x16x32_bf16 v[2:5], v[24:27], v[6:9], 0
	v_cmp_lt_f32_e64 vcc, |v0|, s7
	s_nop 1
	v_cndmask_b32_e32 v103, v1, v0, vcc
	v_lshrrev_b32_e32 v0, 1, v100
	v_mfma_f32_16x16x32_bf16 v[6:9], v[28:31], v[6:9], 0
	v_bfi_b32 v102, 31, v0, v64
	v_add_u32_e32 v96, s20, v102
	v_ashrrev_i32_e32 v97, 31, v96
	s_waitcnt lgkmcnt(0)
	v_mfma_f32_16x16x32_bf16 v[72:75], v[20:23], v[10:13], v[2:5]
	s_nop 2
	ds_read_b128 v[0:3], v33 offset:23040
	v_lshlrev_b64 v[4:5], 12, v[96:97]
	v_mfma_f32_16x16x32_bf16 v[40:43], v[16:19], v[10:13], v[6:9]
	s_nop 2
	v_lshl_add_u64 v[8:9], s[48:49], 0, v[4:5]
	v_lshl_add_u64 v[34:35], v[8:9], 0, s[88:89]
	ds_read_b128 v[8:11], v33 offset:23104
	s_waitcnt lgkmcnt(1)
	v_mfma_f32_16x16x32_bf16 v[4:7], v[24:27], v[0:3], 0
	v_lshl_add_u64 v[34:35], v[34:35], 0, v[184:185]
	v_mfma_f32_16x16x32_bf16 v[12:15], v[28:31], v[0:3], 0
	s_waitcnt lgkmcnt(0)
	v_mfma_f32_16x16x32_bf16 v[68:71], v[20:23], v[8:11], v[4:7]
	global_load_dwordx4 v[0:3], v[34:35], off offset:1584
	s_nop 2
	global_load_dwordx4 v[4:7], v[34:35], off offset:1568
	ds_read_b128 v[64:67], v33 offset:25344
	v_mfma_f32_16x16x32_bf16 v[36:39], v[16:19], v[8:11], v[12:15]
	global_load_dwordx4 v[8:11], v[34:35], off offset:1552
	s_nop 1
	global_load_dwordx4 v[12:15], v[34:35], off offset:1536
	ds_read_b128 v[130:133], v33 offset:25408
	v_lshrrev_b32_e32 v33, 2, v100
	v_and_or_b32 v100, v33, 12, v32
	v_sub_u32_e32 v32, v100, v101
	v_sub_u32_e32 v33, 0, v32
	v_max_i32_e32 v32, v32, v33
	v_cvt_f32_u32_e32 v106, v32
	s_waitcnt lgkmcnt(1)
	v_mfma_f32_16x16x32_bf16 v[120:123], v[24:27], v[64:67], 0
	v_cmp_lt_i32_e32 vcc, v100, v101
	v_or_b32_e32 v109, 1, v100
	s_waitcnt lgkmcnt(0)
	v_mfma_f32_16x16x32_bf16 v[134:137], v[28:31], v[64:67], 0
	v_cndmask_b32_e32 v108, v99, v103, vcc
	v_mul_f32_e32 v106, v108, v106
	v_mul_f32_e32 v106, 0xbfb8aa3b, v106
	v_mfma_f32_16x16x32_bf16 v[64:67], v[20:23], v[130:133], v[120:123]
	v_sad_u32 v108, v109, v101, 0
	v_mfma_f32_16x16x32_bf16 v[32:35], v[16:19], v[130:133], v[134:137]
	v_exp_f32_e32 v130, v106
	v_cvt_f32_u32_e32 v108, v108
	v_cmp_lt_i32_e32 vcc, v109, v101
	s_barrier
	v_mul_f32_e32 v92, v130, v92
	v_cvt_pk_bf16_f32 v106, v92, v92
	v_mul_lo_u32 v92, v100, s4
	v_add_u32_e32 v113, s2, v92
	v_cndmask_b32_e32 v92, v99, v103, vcc
	v_mul_f32_e32 v92, v92, v108
	v_mul_f32_e32 v92, 0xbfb8aa3b, v92
	v_exp_f32_e32 v108, v92
	v_lshlrev_b32_e32 v92, 1, v101
	v_add_u32_e32 v118, v113, v92
	v_mul_f32_e32 v93, v108, v93
	v_or_b32_e32 v108, 2, v100
	v_sad_u32 v111, v108, v101, 0
	v_cvt_f32_u32_e32 v111, v111
	ds_write_b16_d16_hi v118, v106
	v_cmp_lt_i32_e32 vcc, v108, v101
	v_cvt_pk_bf16_f32 v106, v93, v93
	v_add_u32_e32 v114, 0x110, v113
	v_cndmask_b32_e32 v93, v99, v103, vcc
	v_mul_f32_e32 v93, v93, v111
	v_mul_f32_e32 v93, 0xbfb8aa3b, v93
	v_exp_f32_e32 v111, v93
	v_add_u32_e32 v93, v114, v92
	ds_write_b16_d16_hi v93, v106
	v_or_b32_e32 v106, 3, v100
	v_sad_u32 v112, v106, v101, 0
	v_cvt_f32_u32_e32 v112, v112
	v_mul_f32_e32 v94, v111, v94
	v_cmp_lt_i32_e32 vcc, v106, v101
	v_cvt_pk_bf16_f32 v94, v94, v94
	v_or_b32_e32 v123, 16, v100
	v_cndmask_b32_e32 v111, v99, v103, vcc
	v_mul_f32_e32 v111, v111, v112
	v_mul_f32_e32 v111, 0xbfb8aa3b, v111
	v_exp_f32_e32 v111, v111
	v_add_u32_e32 v112, 0x220, v113
	v_add_u32_e32 v120, v112, v92
	ds_write_b16_d16_hi v120, v94
	v_mul_f32_e32 v94, v111, v95
	v_sad_u32 v111, v100, v129, 0
	v_cvt_f32_u32_e32 v111, v111
	v_cmp_lt_i32_e32 vcc, v100, v129
	v_cvt_pk_bf16_f32 v95, v94, v94
	v_or_b32_e32 v122, 17, v100
	v_cndmask_b32_e32 v94, v99, v103, vcc
	v_mul_f32_e32 v94, v94, v111
	v_mul_f32_e32 v94, 0xbfb8aa3b, v94
	v_exp_f32_e32 v121, v94
	v_add_u32_e32 v111, 0x330, v113
	v_add_u32_e32 v94, v111, v92
	ds_write_b16_d16_hi v94, v95
	v_mul_f32_e32 v88, v121, v88
	v_cvt_pk_bf16_f32 v88, v88, v88
	v_sad_u32 v95, v109, v129, 0
	v_cvt_f32_u32_e32 v95, v95
	v_cmp_lt_i32_e32 vcc, v109, v129
	ds_write_b16_d16_hi v118, v88 offset:32
	v_mul_f32_e32 v56, v130, v56
	v_cndmask_b32_e32 v88, v99, v103, vcc
	v_mul_f32_e32 v88, v88, v95
	v_sad_u32 v95, v108, v129, 0
	v_mul_f32_e32 v88, 0xbfb8aa3b, v88
	v_exp_f32_e32 v88, v88
	v_cvt_f32_u32_e32 v95, v95
	v_cmp_lt_i32_e32 vcc, v108, v129
	v_mul_f32_e32 v88, v88, v89
	v_or_b32_e32 v121, 18, v100
	v_cndmask_b32_e32 v89, v99, v103, vcc
	v_mul_f32_e32 v89, v89, v95
	v_mul_f32_e32 v89, 0xbfb8aa3b, v89
	v_exp_f32_e32 v89, v89
	v_cvt_pk_bf16_f32 v88, v88, v88
	ds_write_b16_d16_hi v93, v88 offset:32
	v_mul_f32_e32 v88, v89, v90
	v_cvt_pk_bf16_f32 v88, v88, v88
	v_sad_u32 v89, v106, v129, 0
	v_cvt_f32_u32_e32 v89, v89
	v_cmp_lt_i32_e32 vcc, v106, v129
	ds_write_b16_d16_hi v120, v88 offset:32
	s_nop 0
	v_cndmask_b32_e32 v88, v99, v103, vcc
	v_mul_f32_e32 v88, v88, v89
	v_sad_u32 v89, v100, v128, 0
	v_cvt_f32_u32_e32 v89, v89
	v_cmp_lt_i32_e32 vcc, v100, v128
	v_mul_f32_e32 v88, 0xbfb8aa3b, v88
	v_exp_f32_e32 v88, v88
	v_cndmask_b32_e32 v90, v99, v103, vcc
	v_mul_f32_e32 v89, v90, v89
	v_mul_f32_e32 v89, 0xbfb8aa3b, v89
	v_exp_f32_e32 v89, v89
	v_mul_f32_e32 v88, v88, v91
	v_cvt_pk_bf16_f32 v88, v88, v88
	v_mul_f32_e32 v84, v89, v84
	ds_write_b16_d16_hi v94, v88 offset:32
	v_cvt_pk_bf16_f32 v84, v84, v84
	v_sad_u32 v88, v109, v128, 0
	v_cvt_f32_u32_e32 v88, v88
	v_cmp_lt_i32_e32 vcc, v109, v128
	ds_write_b16_d16_hi v118, v84 offset:64
	s_nop 0
	v_cndmask_b32_e32 v84, v99, v103, vcc
	v_mul_f32_e32 v84, v84, v88
	v_sad_u32 v88, v108, v128, 0
	v_mul_f32_e32 v84, 0xbfb8aa3b, v84
	v_exp_f32_e32 v84, v84
	v_cvt_f32_u32_e32 v88, v88
	v_cmp_lt_i32_e32 vcc, v108, v128
	v_mul_f32_e32 v84, v84, v85
	s_nop 0
	v_cndmask_b32_e32 v85, v99, v103, vcc
	v_mul_f32_e32 v85, v85, v88
	v_mul_f32_e32 v85, 0xbfb8aa3b, v85
	v_exp_f32_e32 v85, v85
	v_cvt_pk_bf16_f32 v84, v84, v84
	ds_write_b16_d16_hi v93, v84 offset:64
	v_mul_f32_e32 v84, v85, v86
	v_cvt_pk_bf16_f32 v84, v84, v84
	v_sad_u32 v85, v106, v128, 0
	v_cvt_f32_u32_e32 v85, v85
	v_cmp_lt_i32_e32 vcc, v106, v128
	ds_write_b16_d16_hi v120, v84 offset:64
	v_add_u32_e32 v88, 0x1200, v107
	v_cndmask_b32_e32 v84, v99, v103, vcc
	v_mul_f32_e32 v84, v84, v85
	v_sad_u32 v85, v100, v127, 0
	v_cvt_f32_u32_e32 v85, v85
	v_cmp_lt_i32_e32 vcc, v100, v127
	v_mul_f32_e32 v84, 0xbfb8aa3b, v84
	v_exp_f32_e32 v84, v84
	v_cndmask_b32_e32 v86, v99, v103, vcc
	v_mul_f32_e32 v85, v86, v85
	v_mul_f32_e32 v85, 0xbfb8aa3b, v85
	v_exp_f32_e32 v85, v85
	v_mul_f32_e32 v84, v84, v87
	v_cvt_pk_bf16_f32 v84, v84, v84
	v_mul_f32_e32 v80, v85, v80
	ds_write_b16_d16_hi v94, v84 offset:64
	v_cvt_pk_bf16_f32 v80, v80, v80
	v_sad_u32 v84, v109, v127, 0
	v_cvt_f32_u32_e32 v84, v84
	v_cmp_lt_i32_e32 vcc, v109, v127
	ds_write_b16_d16_hi v118, v80 offset:96
	s_nop 0
	v_cndmask_b32_e32 v80, v99, v103, vcc
	v_mul_f32_e32 v80, v80, v84
	v_sad_u32 v84, v108, v127, 0
	v_mul_f32_e32 v80, 0xbfb8aa3b, v80
	v_exp_f32_e32 v80, v80
	v_cvt_f32_u32_e32 v84, v84
	v_cmp_lt_i32_e32 vcc, v108, v127
	v_mul_f32_e32 v80, v80, v81
	s_nop 0
	v_cndmask_b32_e32 v81, v99, v103, vcc
	v_mul_f32_e32 v81, v81, v84
	v_mul_f32_e32 v81, 0xbfb8aa3b, v81
	v_exp_f32_e32 v81, v81
	v_cvt_pk_bf16_f32 v80, v80, v80
	ds_write_b16_d16_hi v93, v80 offset:96
	v_mul_f32_e32 v80, v81, v82
	v_cvt_pk_bf16_f32 v80, v80, v80
	v_sad_u32 v81, v106, v127, 0
	v_cvt_f32_u32_e32 v81, v81
	v_cmp_lt_i32_e32 vcc, v106, v127
	ds_write_b16_d16_hi v120, v80 offset:96
	s_nop 0
	v_cndmask_b32_e32 v80, v99, v103, vcc
	v_mul_f32_e32 v80, v80, v81
	v_sad_u32 v81, v100, v116, 0
	v_cvt_f32_u32_e32 v81, v81
	v_cmp_lt_i32_e32 vcc, v100, v116
	v_mul_f32_e32 v80, 0xbfb8aa3b, v80
	v_exp_f32_e32 v80, v80
	v_cndmask_b32_e32 v82, v99, v103, vcc
	v_mul_f32_e32 v81, v82, v81
	v_mul_f32_e32 v81, 0xbfb8aa3b, v81
	v_exp_f32_e32 v81, v81
	v_mul_f32_e32 v80, v80, v83
	v_cvt_pk_bf16_f32 v80, v80, v80
	v_mul_f32_e32 v76, v81, v76
	ds_write_b16_d16_hi v94, v80 offset:96
	v_cvt_pk_bf16_f32 v76, v76, v76
	v_sad_u32 v80, v109, v116, 0
	v_cvt_f32_u32_e32 v80, v80
	v_cmp_lt_i32_e32 vcc, v109, v116
	ds_write_b16_d16_hi v118, v76 offset:128
	s_nop 0
	v_cndmask_b32_e32 v76, v99, v103, vcc
	v_mul_f32_e32 v76, v76, v80
	v_sad_u32 v80, v108, v116, 0
	v_mul_f32_e32 v76, 0xbfb8aa3b, v76
	v_exp_f32_e32 v76, v76
	v_cvt_f32_u32_e32 v80, v80
	v_cmp_lt_i32_e32 vcc, v108, v116
	v_mul_f32_e32 v76, v76, v77
	s_nop 0
	v_cndmask_b32_e32 v77, v99, v103, vcc
	v_mul_f32_e32 v77, v77, v80
	v_mul_f32_e32 v77, 0xbfb8aa3b, v77
	v_exp_f32_e32 v77, v77
	v_cvt_pk_bf16_f32 v76, v76, v76
	ds_write_b16_d16_hi v93, v76 offset:128
	v_mul_f32_e32 v76, v77, v78
	v_cvt_pk_bf16_f32 v76, v76, v76
	v_sad_u32 v77, v106, v116, 0
	v_cvt_f32_u32_e32 v77, v77
	v_cmp_lt_i32_e32 vcc, v106, v116
	ds_write_b16_d16_hi v120, v76 offset:128
	s_nop 0
	v_cndmask_b32_e32 v76, v99, v103, vcc
	v_mul_f32_e32 v76, v76, v77
	v_sad_u32 v77, v100, v119, 0
	v_cvt_f32_u32_e32 v77, v77
	v_cmp_lt_i32_e32 vcc, v100, v119
	v_mul_f32_e32 v76, 0xbfb8aa3b, v76
	v_exp_f32_e32 v76, v76
	v_cndmask_b32_e32 v78, v99, v103, vcc
	v_mul_f32_e32 v77, v78, v77
	v_mul_f32_e32 v77, 0xbfb8aa3b, v77
	v_exp_f32_e32 v77, v77
	v_mul_f32_e32 v76, v76, v79
	v_cvt_pk_bf16_f32 v76, v76, v76
	v_mul_f32_e32 v72, v77, v72
	ds_write_b16_d16_hi v94, v76 offset:128
	v_cvt_pk_bf16_f32 v72, v72, v72
	v_sad_u32 v76, v109, v119, 0
	v_cvt_f32_u32_e32 v76, v76
	v_cmp_lt_i32_e32 vcc, v109, v119
	ds_write_b16_d16_hi v118, v72 offset:160
	s_nop 0
	v_cndmask_b32_e32 v72, v99, v103, vcc
	v_mul_f32_e32 v72, v72, v76
	v_sad_u32 v76, v108, v119, 0
	v_mul_f32_e32 v72, 0xbfb8aa3b, v72
	v_exp_f32_e32 v72, v72
	v_cvt_f32_u32_e32 v76, v76
	v_cmp_lt_i32_e32 vcc, v108, v119
	v_mul_f32_e32 v72, v72, v73
	s_nop 0
	v_cndmask_b32_e32 v73, v99, v103, vcc
	v_mul_f32_e32 v73, v73, v76
	v_mul_f32_e32 v73, 0xbfb8aa3b, v73
	v_exp_f32_e32 v73, v73
	v_cvt_pk_bf16_f32 v72, v72, v72
	ds_write_b16_d16_hi v93, v72 offset:160
	v_mul_f32_e32 v72, v73, v74
	v_cvt_pk_bf16_f32 v72, v72, v72
	v_sad_u32 v73, v106, v119, 0
	v_cvt_f32_u32_e32 v73, v73
	v_cmp_lt_i32_e32 vcc, v106, v119
	ds_write_b16_d16_hi v120, v72 offset:160
	s_nop 0
	v_cndmask_b32_e32 v72, v99, v103, vcc
	v_mul_f32_e32 v72, v72, v73
	v_sad_u32 v73, v100, v117, 0
	v_cvt_f32_u32_e32 v73, v73
	v_cmp_lt_i32_e32 vcc, v100, v117
	v_mul_f32_e32 v72, 0xbfb8aa3b, v72
	v_exp_f32_e32 v72, v72
	v_cndmask_b32_e32 v74, v99, v103, vcc
	v_mul_f32_e32 v73, v74, v73
	v_mul_f32_e32 v73, 0xbfb8aa3b, v73
	v_exp_f32_e32 v73, v73
	v_mul_f32_e32 v72, v72, v75
	v_cvt_pk_bf16_f32 v72, v72, v72
	v_mul_f32_e32 v68, v73, v68
	ds_write_b16_d16_hi v94, v72 offset:160
	v_cvt_pk_bf16_f32 v68, v68, v68
	v_sad_u32 v72, v109, v117, 0
	v_cvt_f32_u32_e32 v72, v72
	v_cmp_lt_i32_e32 vcc, v109, v117
	ds_write_b16_d16_hi v118, v68 offset:192
	s_nop 0
	v_cndmask_b32_e32 v68, v99, v103, vcc
	v_mul_f32_e32 v68, v68, v72
	v_sad_u32 v72, v108, v117, 0
	v_mul_f32_e32 v68, 0xbfb8aa3b, v68
	v_exp_f32_e32 v68, v68
	v_cvt_f32_u32_e32 v72, v72
	v_cmp_lt_i32_e32 vcc, v108, v117
	v_mul_f32_e32 v68, v68, v69
	s_nop 0
	v_cndmask_b32_e32 v69, v99, v103, vcc
	v_mul_f32_e32 v69, v69, v72
	v_mul_f32_e32 v69, 0xbfb8aa3b, v69
	v_exp_f32_e32 v69, v69
	v_cvt_pk_bf16_f32 v68, v68, v68
	ds_write_b16_d16_hi v93, v68 offset:192
	v_mul_f32_e32 v68, v69, v70
	v_cvt_pk_bf16_f32 v68, v68, v68
	v_sad_u32 v69, v106, v117, 0
	v_cvt_f32_u32_e32 v69, v69
	v_cmp_lt_i32_e32 vcc, v106, v117
	ds_write_b16_d16_hi v120, v68 offset:192
	s_nop 0
	v_cndmask_b32_e32 v68, v99, v103, vcc
	v_mul_f32_e32 v68, v68, v69
	v_sad_u32 v69, v100, v115, 0
	v_cvt_f32_u32_e32 v69, v69
	v_cmp_lt_i32_e32 vcc, v100, v115
	v_mul_f32_e32 v68, 0xbfb8aa3b, v68
	v_exp_f32_e32 v68, v68
	v_cndmask_b32_e32 v70, v99, v103, vcc
	v_mul_f32_e32 v69, v70, v69
	v_mul_f32_e32 v69, 0xbfb8aa3b, v69
	v_exp_f32_e32 v69, v69
	v_mul_f32_e32 v68, v68, v71
	v_cvt_pk_bf16_f32 v68, v68, v68
	v_mul_f32_e32 v64, v69, v64
	ds_write_b16_d16_hi v94, v68 offset:192
	v_cvt_pk_bf16_f32 v64, v64, v64
	v_sad_u32 v68, v109, v115, 0
	v_cvt_f32_u32_e32 v68, v68
	v_cmp_lt_i32_e32 vcc, v109, v115
	ds_write_b16_d16_hi v118, v64 offset:224
	v_or_b32_e32 v118, 19, v100
	v_cndmask_b32_e32 v64, v99, v103, vcc
	v_mul_f32_e32 v64, v64, v68
	v_sad_u32 v68, v108, v115, 0
	v_mul_f32_e32 v64, 0xbfb8aa3b, v64
	v_exp_f32_e32 v64, v64
	v_cvt_f32_u32_e32 v68, v68
	v_cmp_lt_i32_e32 vcc, v108, v115
	v_mul_f32_e32 v64, v64, v65
	s_nop 0
	v_cndmask_b32_e32 v65, v99, v103, vcc
	v_mul_f32_e32 v65, v65, v68
	v_mul_f32_e32 v65, 0xbfb8aa3b, v65
	v_exp_f32_e32 v65, v65
	v_cvt_pk_bf16_f32 v64, v64, v64
	ds_write_b16_d16_hi v93, v64 offset:224
	v_mul_f32_e32 v64, v65, v66
	v_cvt_pk_bf16_f32 v64, v64, v64
	v_sad_u32 v65, v106, v115, 0
	v_cvt_f32_u32_e32 v65, v65
	v_cmp_lt_i32_e32 vcc, v106, v115
	ds_write_b16_d16_hi v120, v64 offset:224
	v_add_u32_e32 v68, 0x900, v107
	v_cndmask_b32_e32 v64, v99, v103, vcc
	v_mul_f32_e32 v64, v64, v65
	v_sad_u32 v65, v123, v101, 0
	v_cvt_f32_u32_e32 v65, v65
	v_cmp_lt_i32_e32 vcc, v123, v101
	v_mul_f32_e32 v64, 0xbfb8aa3b, v64
	v_exp_f32_e32 v64, v64
	v_cndmask_b32_e32 v66, v99, v103, vcc
	v_mul_f32_e32 v65, v66, v65
	v_mul_f32_e32 v65, 0xbfb8aa3b, v65
	v_exp_f32_e32 v65, v65
	v_mul_f32_e32 v64, v64, v67
	v_cvt_pk_bf16_f32 v64, v64, v64
	v_mul_f32_e32 v60, v65, v60
	ds_write_b16_d16_hi v94, v64 offset:224
	v_cvt_pk_bf16_f32 v64, v60, v60
	v_sad_u32 v60, v122, v101, 0
	v_cvt_f32_u32_e32 v60, v60
	v_cmp_lt_i32_e32 vcc, v122, v101
	v_mul_lo_u32 v65, v123, s4
	v_add_u32_e32 v126, s2, v65
	v_cndmask_b32_e32 v66, v99, v103, vcc
	v_mul_f32_e32 v60, v66, v60
	v_mul_f32_e32 v60, 0xbfb8aa3b, v60
	v_exp_f32_e32 v66, v60
	v_sub_u32_e32 v65, v121, v101
	v_add_u32_e32 v60, v126, v92
	ds_write_b16_d16_hi v60, v64
	v_mul_f32_e32 v61, v66, v61
	v_sub_u32_e32 v66, 0, v65
	v_max_i32_e32 v65, v65, v66
	v_cvt_f32_u32_e32 v65, v65
	v_cmp_lt_i32_e32 vcc, v121, v101
	v_cvt_pk_bf16_f32 v61, v61, v61
	v_add_u32_e32 v125, 0x110, v126
	v_cndmask_b32_e32 v64, v99, v103, vcc
	v_mul_f32_e32 v64, v64, v65
	v_mul_f32_e32 v64, 0xbfb8aa3b, v64
	v_exp_f32_e32 v65, v64
	v_add_u32_e32 v64, v125, v92
	ds_write_b16_d16_hi v64, v61
	v_cmp_lt_i32_e32 vcc, v118, v101
	v_mul_f32_e32 v61, v65, v62
	v_sad_u32 v65, v118, v101, 0
	v_cvt_f32_u32_e32 v65, v65
	v_cvt_pk_bf16_f32 v62, v61, v61
	v_cndmask_b32_e32 v61, v99, v103, vcc
	v_mul_f32_e32 v61, v61, v65
	v_mul_f32_e32 v61, 0xbfb8aa3b, v61
	v_exp_f32_e32 v65, v61
	v_add_u32_e32 v124, 0x220, v126
	v_add_u32_e32 v61, v124, v92
	ds_write_b16_d16_hi v61, v62
	v_mul_f32_e32 v62, v65, v63
	v_add_u32_e32 v120, 0x330, v126
	v_cvt_pk_bf16_f32 v63, v62, v62
	v_add_u32_e32 v62, v120, v92
	ds_write_b16_d16_hi v62, v63
	v_sad_u32 v63, v122, v129, 0
	v_cvt_f32_u32_e32 v63, v63
	v_cmp_lt_i32_e32 vcc, v122, v129
	s_nop 1
	v_cndmask_b32_e32 v65, v99, v103, vcc
	v_mul_f32_e32 v63, v65, v63
	v_mul_f32_e32 v63, 0xbfb8aa3b, v63
	v_exp_f32_e32 v63, v63
	v_cvt_pk_bf16_f32 v56, v56, v56
	ds_write_b16_d16_hi v60, v56 offset:32
	v_mul_f32_e32 v56, v63, v57
	v_cvt_pk_bf16_f32 v56, v56, v56
	v_sad_u32 v57, v121, v129, 0
	v_cvt_f32_u32_e32 v57, v57
	v_cmp_lt_i32_e32 vcc, v121, v129
	ds_write_b16_d16_hi v64, v56 offset:32
	s_nop 0
	v_cndmask_b32_e32 v56, v99, v103, vcc
	v_mul_f32_e32 v56, v56, v57
	v_sub_u32_e32 v57, v118, v129
	v_mul_f32_e32 v56, 0xbfb8aa3b, v56
	v_sub_u32_e32 v63, 0, v57
	v_exp_f32_e32 v56, v56
	v_max_i32_e32 v57, v57, v63
	v_cvt_f32_u32_e32 v57, v57
	v_cmp_lt_i32_e32 vcc, v118, v129
	v_mul_f32_e32 v56, v56, v58
	s_nop 0
	v_cndmask_b32_e32 v58, v99, v103, vcc
	v_mul_f32_e32 v57, v58, v57
	v_mul_f32_e32 v57, 0xbfb8aa3b, v57
	v_exp_f32_e32 v57, v57
	v_cvt_pk_bf16_f32 v56, v56, v56
	ds_write_b16_d16_hi v61, v56 offset:32
	v_mul_f32_e32 v56, v57, v59
	v_cvt_pk_bf16_f32 v56, v56, v56
	v_sad_u32 v57, v123, v128, 0
	v_cvt_f32_u32_e32 v57, v57
	v_cmp_lt_i32_e32 vcc, v123, v128
	ds_write_b16_d16_hi v62, v56 offset:32
	s_nop 0
	v_cndmask_b32_e32 v56, v99, v103, vcc
	v_mul_f32_e32 v56, v56, v57
	v_sub_u32_e32 v57, v122, v128
	v_mul_f32_e32 v56, 0xbfb8aa3b, v56
	v_sub_u32_e32 v58, 0, v57
	v_exp_f32_e32 v56, v56
	v_max_i32_e32 v57, v57, v58
	v_cvt_f32_u32_e32 v57, v57
	v_cmp_lt_i32_e32 vcc, v122, v128
	v_mul_f32_e32 v52, v56, v52
	s_nop 0
	v_cndmask_b32_e32 v56, v99, v103, vcc
	v_mul_f32_e32 v56, v56, v57
	v_mul_f32_e32 v56, 0xbfb8aa3b, v56
	v_exp_f32_e32 v56, v56
	v_cvt_pk_bf16_f32 v52, v52, v52
	ds_write_b16_d16_hi v60, v52 offset:64
	v_mul_f32_e32 v52, v56, v53
	v_cvt_pk_bf16_f32 v52, v52, v52
	v_sad_u32 v53, v121, v128, 0
	v_cvt_f32_u32_e32 v53, v53
	v_cmp_lt_i32_e32 vcc, v121, v128
	ds_write_b16_d16_hi v64, v52 offset:64
	s_nop 0
	v_cndmask_b32_e32 v52, v99, v103, vcc
	v_mul_f32_e32 v52, v52, v53
	v_sub_u32_e32 v53, v118, v128
	v_mul_f32_e32 v52, 0xbfb8aa3b, v52
	v_sub_u32_e32 v56, 0, v53
	v_exp_f32_e32 v52, v52
	v_max_i32_e32 v53, v53, v56
	v_cvt_f32_u32_e32 v53, v53
	v_cmp_lt_i32_e32 vcc, v118, v128
	v_mul_f32_e32 v52, v52, v54
	s_nop 0
	v_cndmask_b32_e32 v54, v99, v103, vcc
	v_mul_f32_e32 v53, v54, v53
	v_mul_f32_e32 v53, 0xbfb8aa3b, v53
	v_exp_f32_e32 v53, v53
	v_cvt_pk_bf16_f32 v52, v52, v52
	ds_write_b16_d16_hi v61, v52 offset:64
	v_mul_f32_e32 v52, v53, v55
	v_cvt_pk_bf16_f32 v52, v52, v52
	v_sad_u32 v53, v123, v127, 0
	v_cvt_f32_u32_e32 v53, v53
	v_cmp_lt_i32_e32 vcc, v123, v127
	ds_write_b16_d16_hi v62, v52 offset:64
	s_nop 0
	v_cndmask_b32_e32 v52, v99, v103, vcc
	v_mul_f32_e32 v52, v52, v53
	v_sad_u32 v53, v122, v127, 0
	v_mul_f32_e32 v52, 0xbfb8aa3b, v52
	v_exp_f32_e32 v52, v52
	v_cvt_f32_u32_e32 v53, v53
	v_cmp_lt_i32_e32 vcc, v122, v127
	v_mul_f32_e32 v48, v52, v48
	s_nop 0
	v_cndmask_b32_e32 v52, v99, v103, vcc
	v_mul_f32_e32 v52, v52, v53
	v_mul_f32_e32 v52, 0xbfb8aa3b, v52
	v_exp_f32_e32 v52, v52
	v_cvt_pk_bf16_f32 v48, v48, v48
	ds_write_b16_d16_hi v60, v48 offset:96
	v_mul_f32_e32 v48, v52, v49
	v_cvt_pk_bf16_f32 v48, v48, v48
	v_sad_u32 v49, v121, v127, 0
	v_cvt_f32_u32_e32 v49, v49
	v_cmp_lt_i32_e32 vcc, v121, v127
	ds_write_b16_d16_hi v64, v48 offset:96
	s_nop 0
	v_cndmask_b32_e32 v48, v99, v103, vcc
	v_mul_f32_e32 v48, v48, v49
	v_sad_u32 v49, v118, v127, 0
	v_mul_f32_e32 v48, 0xbfb8aa3b, v48
	v_exp_f32_e32 v48, v48
	v_cvt_f32_u32_e32 v49, v49
	v_cmp_lt_i32_e32 vcc, v118, v127
	v_mul_f32_e32 v48, v48, v50
	s_nop 0
	v_cndmask_b32_e32 v50, v99, v103, vcc
	v_mul_f32_e32 v49, v50, v49
	v_mul_f32_e32 v49, 0xbfb8aa3b, v49
	v_exp_f32_e32 v49, v49
	v_cvt_pk_bf16_f32 v48, v48, v48
	ds_write_b16_d16_hi v61, v48 offset:96
	v_mul_f32_e32 v48, v49, v51
	v_cvt_pk_bf16_f32 v48, v48, v48
	v_sad_u32 v49, v123, v116, 0
	v_cvt_f32_u32_e32 v49, v49
	v_cmp_lt_i32_e32 vcc, v123, v116
	ds_write_b16_d16_hi v62, v48 offset:96
	s_nop 0
	v_cndmask_b32_e32 v48, v99, v103, vcc
	v_mul_f32_e32 v48, v48, v49
	v_sad_u32 v49, v122, v116, 0
	v_mul_f32_e32 v48, 0xbfb8aa3b, v48
	v_exp_f32_e32 v48, v48
	v_cvt_f32_u32_e32 v49, v49
	v_cmp_lt_i32_e32 vcc, v122, v116
	v_mul_f32_e32 v44, v48, v44
	s_nop 0
	v_cndmask_b32_e32 v48, v99, v103, vcc
	v_mul_f32_e32 v48, v48, v49
	v_mul_f32_e32 v48, 0xbfb8aa3b, v48
	v_exp_f32_e32 v48, v48
	v_cvt_pk_bf16_f32 v44, v44, v44
	ds_write_b16_d16_hi v60, v44 offset:128
	v_mul_f32_e32 v44, v48, v45
	v_cvt_pk_bf16_f32 v44, v44, v44
	v_sad_u32 v45, v121, v116, 0
	v_cvt_f32_u32_e32 v45, v45
	v_cmp_lt_i32_e32 vcc, v121, v116
	ds_write_b16_d16_hi v64, v44 offset:128
	s_nop 0
	v_cndmask_b32_e32 v44, v99, v103, vcc
	v_mul_f32_e32 v44, v44, v45
	v_sad_u32 v45, v118, v116, 0
	v_mul_f32_e32 v44, 0xbfb8aa3b, v44
	v_exp_f32_e32 v44, v44
	v_cvt_f32_u32_e32 v45, v45
	v_cmp_lt_i32_e32 vcc, v118, v116
	v_mul_f32_e32 v44, v44, v46
	s_nop 0
	v_cndmask_b32_e32 v46, v99, v103, vcc
	v_mul_f32_e32 v45, v46, v45
	v_mul_f32_e32 v45, 0xbfb8aa3b, v45
	v_exp_f32_e32 v45, v45
	v_cvt_pk_bf16_f32 v44, v44, v44
	ds_write_b16_d16_hi v61, v44 offset:128
	v_mul_f32_e32 v44, v45, v47
	v_cvt_pk_bf16_f32 v44, v44, v44
	v_sad_u32 v45, v123, v119, 0
	v_cvt_f32_u32_e32 v45, v45
	v_cmp_lt_i32_e32 vcc, v123, v119
	ds_write_b16_d16_hi v62, v44 offset:128
	s_nop 0
	v_cndmask_b32_e32 v44, v99, v103, vcc
	v_mul_f32_e32 v44, v44, v45
	v_sub_u32_e32 v45, v122, v119
	v_mul_f32_e32 v44, 0xbfb8aa3b, v44
	v_sub_u32_e32 v46, 0, v45
	v_exp_f32_e32 v44, v44
	v_max_i32_e32 v45, v45, v46
	v_cvt_f32_u32_e32 v45, v45
	v_cmp_lt_i32_e32 vcc, v122, v119
	v_mul_f32_e32 v40, v44, v40
	s_nop 0
	v_cndmask_b32_e32 v44, v99, v103, vcc
	v_mul_f32_e32 v44, v44, v45
	v_mul_f32_e32 v44, 0xbfb8aa3b, v44
	v_exp_f32_e32 v44, v44
	v_cvt_pk_bf16_f32 v40, v40, v40
	ds_write_b16_d16_hi v60, v40 offset:160
	v_mul_f32_e32 v40, v44, v41
	v_cvt_pk_bf16_f32 v40, v40, v40
	v_sad_u32 v41, v121, v119, 0
	v_cvt_f32_u32_e32 v41, v41
	v_cmp_lt_i32_e32 vcc, v121, v119
	ds_write_b16_d16_hi v64, v40 offset:160
	s_nop 0
	v_cndmask_b32_e32 v40, v99, v103, vcc
	v_mul_f32_e32 v40, v40, v41
	v_sub_u32_e32 v41, v118, v119
	v_mul_f32_e32 v40, 0xbfb8aa3b, v40
	v_sub_u32_e32 v44, 0, v41
	v_exp_f32_e32 v40, v40
	v_max_i32_e32 v41, v41, v44
	v_cvt_f32_u32_e32 v41, v41
	v_cmp_lt_i32_e32 vcc, v118, v119
	v_mul_f32_e32 v40, v40, v42
	s_nop 0
	v_cndmask_b32_e32 v42, v99, v103, vcc
	v_mul_f32_e32 v41, v42, v41
	v_mul_f32_e32 v41, 0xbfb8aa3b, v41
	v_exp_f32_e32 v41, v41
	v_cvt_pk_bf16_f32 v40, v40, v40
	ds_write_b16_d16_hi v61, v40 offset:160
	v_mul_f32_e32 v40, v41, v43
	v_cvt_pk_bf16_f32 v40, v40, v40
	v_sad_u32 v41, v123, v117, 0
	v_cvt_f32_u32_e32 v41, v41
	v_cmp_lt_i32_e32 vcc, v123, v117
	ds_write_b16_d16_hi v62, v40 offset:160
	s_nop 0
	v_cndmask_b32_e32 v40, v99, v103, vcc
	v_mul_f32_e32 v40, v40, v41
	v_sad_u32 v41, v122, v117, 0
	v_mul_f32_e32 v40, 0xbfb8aa3b, v40
	v_exp_f32_e32 v40, v40
	v_cvt_f32_u32_e32 v41, v41
	v_cmp_lt_i32_e32 vcc, v122, v117
	v_mul_f32_e32 v36, v40, v36
	s_nop 0
	v_cndmask_b32_e32 v40, v99, v103, vcc
	v_mul_f32_e32 v40, v40, v41
	v_mul_f32_e32 v40, 0xbfb8aa3b, v40
	v_exp_f32_e32 v40, v40
	v_cvt_pk_bf16_f32 v36, v36, v36
	ds_write_b16_d16_hi v60, v36 offset:192
	v_mul_f32_e32 v36, v40, v37
	v_cvt_pk_bf16_f32 v36, v36, v36
	v_sad_u32 v37, v121, v117, 0
	v_cvt_f32_u32_e32 v37, v37
	v_cmp_lt_i32_e32 vcc, v121, v117
	ds_write_b16_d16_hi v64, v36 offset:192
	s_nop 0
	v_cndmask_b32_e32 v36, v99, v103, vcc
	v_mul_f32_e32 v36, v36, v37
	v_sad_u32 v37, v118, v117, 0
	v_mul_f32_e32 v36, 0xbfb8aa3b, v36
	v_exp_f32_e32 v36, v36
	v_cvt_f32_u32_e32 v37, v37
	v_cmp_lt_i32_e32 vcc, v118, v117
	v_mul_f32_e32 v36, v36, v38
	v_mad_u64_u32 v[116:117], s[22:23], v105, s4, v[98:99]
	v_cndmask_b32_e32 v38, v99, v103, vcc
	v_mul_f32_e32 v37, v38, v37
	v_mul_f32_e32 v37, 0xbfb8aa3b, v37
	v_exp_f32_e32 v37, v37
	v_cvt_pk_bf16_f32 v36, v36, v36
	ds_write_b16_d16_hi v61, v36 offset:192
	v_mul_f32_e32 v36, v37, v39
	v_cvt_pk_bf16_f32 v36, v36, v36
	v_sad_u32 v37, v123, v115, 0
	v_cvt_f32_u32_e32 v37, v37
	v_cmp_lt_i32_e32 vcc, v123, v115
	ds_write_b16_d16_hi v62, v36 offset:192
	s_nop 0
	v_cndmask_b32_e32 v36, v99, v103, vcc
	v_mul_f32_e32 v36, v36, v37
	v_sub_u32_e32 v37, v122, v115
	v_mul_f32_e32 v36, 0xbfb8aa3b, v36
	v_sub_u32_e32 v38, 0, v37
	v_exp_f32_e32 v36, v36
	v_max_i32_e32 v37, v37, v38
	v_cvt_f32_u32_e32 v37, v37
	v_cmp_lt_i32_e32 vcc, v122, v115
	v_mul_f32_e32 v32, v36, v32
	s_nop 0
	v_cndmask_b32_e32 v36, v99, v103, vcc
	v_mul_f32_e32 v36, v36, v37
	v_mul_f32_e32 v36, 0xbfb8aa3b, v36
	v_exp_f32_e32 v36, v36
	v_cvt_pk_bf16_f32 v32, v32, v32
	ds_write_b16_d16_hi v60, v32 offset:224
	v_mul_f32_e32 v32, v36, v33
	v_cvt_pk_bf16_f32 v32, v32, v32
	v_sad_u32 v33, v121, v115, 0
	v_cvt_f32_u32_e32 v33, v33
	v_cmp_lt_i32_e32 vcc, v121, v115
	ds_write_b16_d16_hi v64, v32 offset:224
	s_nop 0
	v_cndmask_b32_e32 v32, v99, v103, vcc
	v_mul_f32_e32 v32, v32, v33
	v_sub_u32_e32 v33, v118, v115
	v_mul_f32_e32 v32, 0xbfb8aa3b, v32
	v_sub_u32_e32 v36, 0, v33
	v_exp_f32_e32 v32, v32
	v_max_i32_e32 v33, v33, v36
	v_cvt_f32_u32_e32 v33, v33
	v_cmp_lt_i32_e32 vcc, v118, v115
	v_mul_f32_e32 v32, v32, v34
	s_nop 0
	v_cndmask_b32_e32 v34, v99, v103, vcc
	v_mul_f32_e32 v33, v34, v33
	v_mul_f32_e32 v33, 0xbfb8aa3b, v33
	v_exp_f32_e32 v33, v33
	v_cvt_pk_bf16_f32 v32, v32, v32
	ds_write_b16_d16_hi v61, v32 offset:224
	v_mul_f32_e32 v32, v33, v35
	v_cvt_pk_bf16_f32 v32, v32, v32
	ds_write_b16_d16_hi v62, v32 offset:224
	s_waitcnt lgkmcnt(0)
	s_barrier
	ds_read_b128 v[32:35], v107 offset:54272
	ds_read_b128 v[48:51], v107 offset:54336
	ds_read_b128 v[40:43], v107 offset:63488
	ds_read_b128 v[52:55], v107 offset:63552
	s_waitcnt lgkmcnt(3)
	v_mfma_f32_16x16x32_bf16 v[36:39], v[24:27], v[32:35], 0
	ds_read_b128 v[72:75], v107 offset:56640
	ds_read_b128 v[76:79], v68 offset:63552
	ds_read_b128 v[84:87], v107 offset:58944
	s_waitcnt lgkmcnt(4)
	v_mfma_f32_16x16x32_bf16 v[44:47], v[24:27], v[40:43], 0
	ds_read_b128 v[128:131], v107 offset:61248
	ds_read_b128 v[148:151], v116 offset:64
	ds_read_b128 v[144:147], v116 offset:4352
	v_mfma_f32_16x16x32_bf16 v[32:35], v[28:31], v[32:35], 0
	ds_read_b128 v[164:167], v116 offset:4544
	v_cmp_lt_i32_e32 vcc, v235, v229
	v_mfma_f32_16x16x32_bf16 v[40:43], v[28:31], v[40:43], 0
	v_mfma_f32_16x16x32_bf16 v[56:59], v[20:23], v[48:51], v[36:39]
	v_mfma_f32_16x16x32_bf16 v[36:39], v[16:19], v[48:51], v[32:35]
	ds_read_b128 v[48:51], v68 offset:63488
	s_waitcnt lgkmcnt(8)
	v_mfma_f32_16x16x32_bf16 v[32:35], v[16:19], v[52:55], v[40:43]
	s_nop 2
	ds_read_b128 v[40:43], v107 offset:56576
	v_mfma_f32_16x16x32_bf16 v[60:63], v[20:23], v[52:55], v[44:47]
	s_waitcnt lgkmcnt(0)
	v_mfma_f32_16x16x32_bf16 v[44:47], v[24:27], v[40:43], 0
	v_mfma_f32_16x16x32_bf16 v[52:55], v[24:27], v[48:51], 0
	v_mfma_f32_16x16x32_bf16 v[40:43], v[28:31], v[40:43], 0
	v_mfma_f32_16x16x32_bf16 v[48:51], v[28:31], v[48:51], 0
	v_mfma_f32_16x16x32_bf16 v[64:67], v[20:23], v[72:75], v[44:47]
	v_mfma_f32_16x16x32_bf16 v[44:47], v[16:19], v[72:75], v[40:43]
	ds_read_b128 v[72:75], v88 offset:63488
	ds_read_b128 v[88:91], v88 offset:63552
	v_mfma_f32_16x16x32_bf16 v[40:43], v[16:19], v[76:79], v[48:51]
	s_nop 2
	ds_read_b128 v[48:51], v107 offset:58880
	v_mfma_f32_16x16x32_bf16 v[68:71], v[20:23], v[76:79], v[52:55]
	s_waitcnt lgkmcnt(0)
	v_mfma_f32_16x16x32_bf16 v[52:55], v[24:27], v[48:51], 0
	v_mfma_f32_16x16x32_bf16 v[48:51], v[28:31], v[48:51], 0
	v_mfma_f32_16x16x32_bf16 v[80:83], v[28:31], v[72:75], 0
	v_mfma_f32_16x16x32_bf16 v[76:79], v[24:27], v[72:75], 0
	v_mfma_f32_16x16x32_bf16 v[72:75], v[20:23], v[84:87], v[52:55]
	v_mfma_f32_16x16x32_bf16 v[52:55], v[16:19], v[84:87], v[48:51]
	v_mfma_f32_16x16x32_bf16 v[48:51], v[16:19], v[88:91], v[80:83]
	s_nop 3
	ds_read_b128 v[80:83], v107 offset:61184
	v_mfma_f32_16x16x32_bf16 v[76:79], v[20:23], v[88:91], v[76:79]
	ds_read_b128 v[88:91], v110 offset:63488
	s_waitcnt lgkmcnt(1)
	v_mfma_f32_16x16x32_bf16 v[84:87], v[24:27], v[80:83], 0
	s_waitcnt lgkmcnt(0)
	v_mfma_f32_16x16x32_bf16 v[92:95], v[24:27], v[88:91], 0
	v_mfma_f32_16x16x32_bf16 v[24:27], v[20:23], v[128:131], v[84:87]
	s_nop 4
	ds_read_b128 v[84:87], v110 offset:63552
	v_mfma_f32_16x16x32_bf16 v[80:83], v[28:31], v[80:83], 0
	v_mfma_f32_16x16x32_bf16 v[88:91], v[28:31], v[88:91], 0
	s_waitcnt lgkmcnt(0)
	v_mfma_f32_16x16x32_bf16 v[28:31], v[20:23], v[84:87], v[92:95]
	v_mfma_f32_16x16x32_bf16 v[20:23], v[16:19], v[128:131], v[80:83]
	s_nop 3
	ds_read_b128 v[80:83], v116
	v_mfma_f32_16x16x32_bf16 v[16:19], v[16:19], v[84:87], v[88:91]
	v_mul_u32_u24_e32 v84, 0x88, v101
	v_lshl_add_u32 v98, v84, 1, v98
	ds_read_b128 v[84:87], v98 offset:36864
	ds_read_b128 v[92:95], v98 offset:41216
	ds_read_b128 v[132:135], v98 offset:45568
	ds_read_b128 v[156:159], v98 offset:45632
	ds_read_b128 v[140:143], v98 offset:49920
	ds_read_b128 v[160:163], v98 offset:49984
	s_waitcnt lgkmcnt(5)
	v_mfma_f32_16x16x32_bf16 v[88:91], v[80:83], v[84:87], 0
	ds_read_b128 v[152:155], v98 offset:41280
	s_waitcnt lgkmcnt(5)
	v_mfma_f32_16x16x32_bf16 v[128:131], v[80:83], v[92:95], 0
	s_waitcnt lgkmcnt(4)
	v_mfma_f32_16x16x32_bf16 v[136:139], v[80:83], v[132:135], 0
	s_waitcnt lgkmcnt(2)
	v_mfma_f32_16x16x32_bf16 v[80:83], v[80:83], v[140:143], 0
	v_mfma_f32_16x16x32_bf16 v[84:87], v[144:147], v[84:87], 0
	v_mfma_f32_16x16x32_bf16 v[92:95], v[144:147], v[92:95], 0
	v_mfma_f32_16x16x32_bf16 v[132:135], v[144:147], v[132:135], 0
	v_mfma_f32_16x16x32_bf16 v[140:143], v[144:147], v[140:143], 0
	ds_read_b128 v[144:147], v98 offset:36928
	s_waitcnt lgkmcnt(0)
	v_mfma_f32_16x16x32_bf16 v[88:91], v[148:151], v[144:147], v[88:91]
	v_mfma_f32_16x16x32_bf16 v[128:131], v[148:151], v[152:155], v[128:131]
	v_mfma_f32_16x16x32_bf16 v[136:139], v[148:151], v[156:159], v[136:139]
	v_mfma_f32_16x16x32_bf16 v[80:83], v[148:151], v[160:163], v[80:83]
	ds_read_b128 v[148:151], v116 offset:4416
	s_waitcnt lgkmcnt(0)
	v_mfma_f32_16x16x32_bf16 v[84:87], v[148:151], v[144:147], v[84:87]
	ds_read_b128 v[144:147], v116 offset:128
	v_mfma_f32_16x16x32_bf16 v[92:95], v[148:151], v[152:155], v[92:95]
	ds_read_b128 v[152:155], v98 offset:41344
	v_mfma_f32_16x16x32_bf16 v[132:135], v[148:151], v[156:159], v[132:135]
	ds_read_b128 v[156:159], v98 offset:45696
	v_mfma_f32_16x16x32_bf16 v[140:143], v[148:151], v[160:163], v[140:143]
	ds_read_b128 v[148:151], v98 offset:36992
	ds_read_b128 v[160:163], v98 offset:50048
	s_waitcnt lgkmcnt(1)
	v_mfma_f32_16x16x32_bf16 v[88:91], v[144:147], v[148:151], v[88:91]
	v_mfma_f32_16x16x32_bf16 v[128:131], v[144:147], v[152:155], v[128:131]
	v_mfma_f32_16x16x32_bf16 v[136:139], v[144:147], v[156:159], v[136:139]
	s_waitcnt lgkmcnt(0)
	v_mfma_f32_16x16x32_bf16 v[80:83], v[144:147], v[160:163], v[80:83]
	ds_read_b128 v[144:147], v116 offset:4480
	s_waitcnt lgkmcnt(0)
	v_mfma_f32_16x16x32_bf16 v[84:87], v[144:147], v[148:151], v[84:87]
	ds_read_b128 v[148:151], v116 offset:192
	v_mfma_f32_16x16x32_bf16 v[92:95], v[144:147], v[152:155], v[92:95]
	v_mfma_f32_16x16x32_bf16 v[132:135], v[144:147], v[156:159], v[132:135]
	ds_read_b128 v[156:159], v98 offset:45760
	v_mfma_f32_16x16x32_bf16 v[140:143], v[144:147], v[160:163], v[140:143]
	ds_read_b128 v[144:147], v98 offset:37056
	ds_read_b128 v[160:163], v98 offset:50112
	s_waitcnt lgkmcnt(1)
	v_mfma_f32_16x16x32_bf16 v[152:155], v[148:151], v[144:147], v[88:91]
	s_nop 2
	ds_read_b128 v[88:91], v98 offset:41408
	s_waitcnt lgkmcnt(0)
	v_mfma_f32_16x16x32_bf16 v[128:131], v[148:151], v[88:91], v[128:131]
	v_mfma_f32_16x16x32_bf16 v[88:91], v[164:167], v[88:91], v[92:95]
	s_nop 2
	v_cvt_f32_i32_e32 v92, v109
	v_sub_u32_e32 v93, 0x80, v100
	v_cvt_f32_i32_e32 v93, v93
	v_mfma_f32_16x16x32_bf16 v[136:139], v[148:151], v[156:159], v[136:139]
	v_mul_f32_e32 v92, v92, v99
	v_mul_f32_e32 v92, 0xbfb8aa3b, v92
	v_exp_f32_e32 v98, v92
	v_mul_f32_e32 v92, v93, v103
	v_mul_f32_e32 v92, 0xbfb8aa3b, v92
	v_exp_f32_e32 v105, v92
	v_fma_f32 v56, v98, v56, v152
	v_fma_f32 v64, v98, v64, v128
	v_mfma_f32_16x16x32_bf16 v[148:151], v[148:151], v[160:163], v[80:83]
	v_fmac_f32_e32 v56, v105, v60
	v_lshlrev_b32_e32 v60, 2, v101
	v_add_u32_e32 v101, v113, v60
	v_fmac_f32_e32 v64, v105, v68
	ds_write2_b32 v101, v56, v64 offset1:16
	v_cvt_f32_i32_e32 v64, v108
	v_sub_u32_e32 v68, 0x80, v109
	v_cvt_f32_i32_e32 v68, v68
	v_fma_f32 v56, v98, v72, v136
	v_mul_f32_e32 v64, v64, v99
	v_mul_f32_e32 v64, 0xbfb8aa3b, v64
	v_mul_f32_e32 v68, v68, v103
	v_exp_f32_e32 v64, v64
	v_mul_f32_e32 v68, 0xbfb8aa3b, v68
	v_exp_f32_e32 v68, v68
	v_fma_f32 v24, v98, v24, v148
	v_fmac_f32_e32 v56, v105, v76
	v_fmac_f32_e32 v24, v105, v28
	ds_write2_b32 v101, v56, v24 offset0:32 offset1:48
	v_fma_f32 v24, v64, v57, v153
	v_fma_f32 v56, v64, v65, v129
	v_fmac_f32_e32 v24, v68, v61
	v_add_u32_e32 v28, v114, v60
	v_fmac_f32_e32 v56, v68, v69
	ds_write2_b32 v28, v24, v56 offset1:16
	v_cvt_f32_i32_e32 v56, v106
	v_sub_u32_e32 v57, 0x80, v108
	v_cvt_f32_i32_e32 v57, v57
	v_fma_f32 v24, v64, v73, v137
	v_mul_f32_e32 v56, v56, v99
	v_mul_f32_e32 v56, 0xbfb8aa3b, v56
	v_mul_f32_e32 v57, v57, v103
	v_exp_f32_e32 v56, v56
	v_mul_f32_e32 v57, 0xbfb8aa3b, v57
	v_exp_f32_e32 v57, v57
	v_fma_f32 v25, v64, v25, v149
	v_fmac_f32_e32 v24, v68, v77
	v_fmac_f32_e32 v25, v68, v29
	ds_write2_b32 v28, v24, v25 offset0:32 offset1:48
	v_fma_f32 v24, v56, v58, v154
	v_fma_f32 v28, v56, v66, v130
	v_fmac_f32_e32 v24, v57, v62
	v_add_u32_e32 v25, v112, v60
	v_fmac_f32_e32 v28, v57, v70
	ds_write2_b32 v25, v24, v28 offset1:16
	v_add_u32_e32 v28, 4, v100
	v_fma_f32 v24, v56, v74, v138
	v_cvt_f32_i32_e32 v28, v28
	v_fma_f32 v26, v56, v26, v150
	v_sub_u32_e32 v29, 0x80, v106
	v_fmac_f32_e32 v24, v57, v78
	v_cvt_f32_i32_e32 v29, v29
	v_fmac_f32_e32 v26, v57, v30
	ds_write2_b32 v25, v24, v26 offset0:32 offset1:48
	v_cvt_f32_i32_e32 v25, v122
	v_sub_u32_e32 v26, 0x80, v123
	v_cvt_f32_i32_e32 v26, v26
	v_mul_f32_e32 v28, v28, v99
	v_mul_f32_e32 v28, 0xbfb8aa3b, v28
	v_mul_f32_e32 v29, v29, v103
	v_exp_f32_e32 v28, v28
	v_mul_f32_e32 v29, 0xbfb8aa3b, v29
	v_mul_f32_e32 v25, v25, v99
	v_exp_f32_e32 v29, v29
	v_mul_f32_e32 v25, 0xbfb8aa3b, v25
	v_mul_f32_e32 v26, v26, v103
	v_mfma_f32_16x16x32_bf16 v[84:87], v[164:167], v[144:147], v[84:87]
	v_exp_f32_e32 v25, v25
	v_mul_f32_e32 v26, 0xbfb8aa3b, v26
	v_exp_f32_e32 v26, v26
	v_mfma_f32_16x16x32_bf16 v[80:83], v[164:167], v[156:159], v[132:135]
	v_fmac_f32_e32 v155, v28, v59
	v_fmac_f32_e32 v131, v28, v67
	v_fmac_f32_e32 v139, v28, v75
	v_mfma_f32_16x16x32_bf16 v[92:95], v[164:167], v[160:163], v[140:143]
	v_fmac_f32_e32 v151, v28, v27
	v_fmac_f32_e32 v155, v29, v63
	v_add_u32_e32 v24, v111, v60
	v_fmac_f32_e32 v131, v29, v71
	v_fmac_f32_e32 v139, v29, v79
	v_fmac_f32_e32 v151, v29, v31
	ds_write2_b32 v24, v155, v131 offset1:16
	ds_write2_b32 v24, v139, v151 offset0:32 offset1:48
	v_fma_f32 v24, v25, v36, v84
	v_fma_f32 v28, v25, v44, v88
	v_fmac_f32_e32 v24, v26, v32
	v_add_u32_e32 v27, v126, v60
	v_fmac_f32_e32 v28, v26, v40
	ds_write2_b32 v27, v24, v28 offset1:16
	v_fma_f32 v24, v25, v52, v80
	v_cvt_f32_i32_e32 v28, v121
	v_fma_f32 v20, v25, v20, v92
	v_sub_u32_e32 v25, 0x80, v122
	v_cvt_f32_i32_e32 v25, v25
	v_mul_f32_e32 v28, v28, v99
	v_mul_f32_e32 v28, 0xbfb8aa3b, v28
	v_exp_f32_e32 v28, v28
	v_mul_f32_e32 v25, v25, v103
	v_mul_f32_e32 v25, 0xbfb8aa3b, v25
	v_exp_f32_e32 v25, v25
	v_fmac_f32_e32 v24, v26, v48
	v_fmac_f32_e32 v20, v26, v16
	ds_write2_b32 v27, v24, v20 offset0:32 offset1:48
	v_fma_f32 v16, v28, v37, v85
	v_fma_f32 v24, v28, v45, v89
	v_fmac_f32_e32 v16, v25, v33
	v_add_u32_e32 v20, v125, v60
	v_fmac_f32_e32 v24, v25, v41
	ds_write2_b32 v20, v16, v24 offset1:16
	v_cvt_f32_i32_e32 v24, v118
	v_sub_u32_e32 v26, 0x80, v121
	v_cvt_f32_i32_e32 v26, v26
	v_fma_f32 v16, v28, v53, v81
	v_mul_f32_e32 v24, v24, v99
	v_mul_f32_e32 v24, 0xbfb8aa3b, v24
	v_mul_f32_e32 v26, v26, v103
	v_exp_f32_e32 v24, v24
	v_mul_f32_e32 v26, 0xbfb8aa3b, v26
	v_exp_f32_e32 v26, v26
	v_fma_f32 v21, v28, v21, v93
	v_fmac_f32_e32 v16, v25, v49
	v_fmac_f32_e32 v21, v25, v17
	ds_write2_b32 v20, v16, v21 offset0:32 offset1:48
	v_fma_f32 v16, v24, v38, v86
	v_fma_f32 v20, v24, v46, v90
	v_fmac_f32_e32 v16, v26, v34
	v_add_u32_e32 v17, v124, v60
	v_fmac_f32_e32 v20, v26, v42
	ds_write2_b32 v17, v16, v20 offset1:16
	v_add_u32_e32 v20, 20, v100
	v_cvt_f32_i32_e32 v20, v20
	v_fma_f32 v21, v24, v22, v94
	v_sub_u32_e32 v22, 0x80, v118
	v_cvt_f32_i32_e32 v22, v22
	v_mul_f32_e32 v20, v20, v99
	v_mul_f32_e32 v20, 0xbfb8aa3b, v20
	v_exp_f32_e32 v20, v20
	v_mul_f32_e32 v22, v22, v103
	v_mul_f32_e32 v22, 0xbfb8aa3b, v22
	v_exp_f32_e32 v22, v22
	v_fma_f32 v16, v24, v54, v82
	v_fmac_f32_e32 v16, v26, v50
	v_fmac_f32_e32 v21, v26, v18
	v_fmac_f32_e32 v87, v20, v39
	v_fmac_f32_e32 v91, v20, v47
	v_fmac_f32_e32 v83, v20, v55
	v_fmac_f32_e32 v95, v20, v23
	ds_write2_b32 v17, v16, v21 offset0:32 offset1:48
	v_fmac_f32_e32 v87, v22, v35
	v_add_u32_e32 v16, v120, v60
	v_fmac_f32_e32 v91, v22, v43
	v_fmac_f32_e32 v83, v22, v51
	v_fmac_f32_e32 v95, v22, v19
	ds_write2_b32 v16, v87, v91 offset1:16
	ds_write2_b32 v16, v83, v95 offset0:32 offset1:48
	v_mul_lo_u32 v16, v102, s4
	v_lshlrev_b32_e32 v17, 2, v104
	v_add3_u32 v44, s2, v16, v17
	s_waitcnt lgkmcnt(0)
	s_barrier
	ds_read_b128 v[36:39], v44
	ds_read_b128 v[32:35], v44 offset:16
	ds_read_b128 v[28:31], v44 offset:32
	ds_read_b128 v[24:27], v44 offset:48
	ds_read_b128 v[20:23], v44 offset:64
	ds_read_b128 v[16:19], v44 offset:80
	s_waitcnt lgkmcnt(5)
	v_add_f32_e32 v40, 0, v36
	v_add_f32_e32 v40, v40, v37
	v_add_f32_e32 v40, v40, v38
	v_add_f32_e32 v40, v40, v39
	s_waitcnt lgkmcnt(4)
	v_add_f32_e32 v40, v40, v32
	v_add_f32_e32 v40, v40, v33
	v_add_f32_e32 v40, v40, v34
	v_add_f32_e32 v40, v40, v35
	s_waitcnt lgkmcnt(3)
	v_add_f32_e32 v40, v40, v28
	v_add_f32_e32 v40, v40, v29
	v_add_f32_e32 v40, v40, v30
	v_add_f32_e32 v40, v40, v31
	s_waitcnt lgkmcnt(2)
	v_add_f32_e32 v40, v40, v24
	v_add_f32_e32 v40, v40, v25
	v_add_f32_e32 v40, v40, v26
	v_add_f32_e32 v40, v40, v27
	s_waitcnt lgkmcnt(1)
	v_add_f32_e32 v40, v40, v20
	v_add_f32_e32 v40, v40, v21
	v_add_f32_e32 v40, v40, v22
	v_add_f32_e32 v40, v40, v23
	s_waitcnt lgkmcnt(0)
	v_add_f32_e32 v40, v40, v16
	v_add_f32_e32 v48, v40, v17
	ds_read_b128 v[40:43], v44 offset:96
	v_cndmask_b32_e32 v45, v228, v235, vcc
	v_add_f32_e32 v48, v48, v18
	v_lshlrev_b32_e32 v49, 2, v45
	ds_read_b128 v[44:47], v44 offset:112
	v_add_f32_e32 v48, v48, v19
	s_waitcnt lgkmcnt(1)
	v_add_f32_e32 v48, v48, v40
	v_add_f32_e32 v48, v48, v41
	v_add_f32_e32 v48, v48, v42
	v_add_f32_e32 v48, v48, v43
	s_waitcnt lgkmcnt(0)
	v_add_f32_e32 v48, v48, v44
	v_add_f32_e32 v48, v48, v45
	v_add_f32_e32 v48, v48, v46
	v_add_f32_e32 v48, v48, v47
	ds_bpermute_b32 v50, v49, v48
	v_readlane_b32 s4, v254, 0
	v_readlane_b32 s5, v254, 1
	s_waitcnt lgkmcnt(0)
	v_add_f32_e32 v50, v48, v50
	v_fmamk_f32 v52, v50, 0xbc800000, v37
	v_fmamk_f32 v51, v50, 0xbc800000, v36
	v_mul_f32_e32 v53, v52, v52
	v_fmac_f32_e32 v53, v51, v51
	v_fmamk_f32 v38, v50, 0xbc800000, v38
	v_fmac_f32_e32 v53, v38, v38
	v_fmac_f32_e32 v39, 0xbc800000, v50
	v_fmac_f32_e32 v53, v39, v39
	v_fmamk_f32 v54, v50, 0xbc800000, v32
	v_fmac_f32_e32 v53, v54, v54
	v_fmamk_f32 v55, v50, 0xbc800000, v33
	v_fmac_f32_e32 v53, v55, v55
	v_fmamk_f32 v34, v50, 0xbc800000, v34
	v_fmac_f32_e32 v53, v34, v34
	v_fmac_f32_e32 v35, 0xbc800000, v50
	v_fmac_f32_e32 v53, v35, v35
	v_fmamk_f32 v56, v50, 0xbc800000, v28
	v_fmac_f32_e32 v53, v56, v56
	v_fmamk_f32 v57, v50, 0xbc800000, v29
	v_fmac_f32_e32 v53, v57, v57
	v_fmamk_f32 v30, v50, 0xbc800000, v30
	v_fmac_f32_e32 v53, v30, v30
	v_fmac_f32_e32 v31, 0xbc800000, v50
	v_fmac_f32_e32 v53, v31, v31
	v_fmamk_f32 v58, v50, 0xbc800000, v24
	v_fmac_f32_e32 v53, v58, v58
	v_fmamk_f32 v59, v50, 0xbc800000, v25
	v_fmac_f32_e32 v53, v59, v59
	v_fmamk_f32 v26, v50, 0xbc800000, v26
	v_fmac_f32_e32 v53, v26, v26
	v_fmac_f32_e32 v27, 0xbc800000, v50
	v_fmac_f32_e32 v53, v27, v27
	v_fmamk_f32 v60, v50, 0xbc800000, v20
	v_fmac_f32_e32 v53, v60, v60
	v_fmamk_f32 v61, v50, 0xbc800000, v21
	v_fmac_f32_e32 v53, v61, v61
	v_fmamk_f32 v22, v50, 0xbc800000, v22
	v_fmac_f32_e32 v53, v22, v22
	v_fmac_f32_e32 v23, 0xbc800000, v50
	v_mul_f32_e32 v48, 0x3c800000, v50
	v_fmac_f32_e32 v53, v23, v23
	v_fmamk_f32 v62, v50, 0xbc800000, v16
	v_fmac_f32_e32 v53, v62, v62
	v_fmac_f32_e32 v17, 0xbc800000, v50
	v_pk_add_f32 v[36:37], v[18:19], v[48:49] op_sel_hi:[1,0] neg_lo:[0,1] neg_hi:[0,1]
	v_fmac_f32_e32 v53, v17, v17
	v_pk_mul_f32 v[18:19], v[36:37], v[36:37]
	v_pk_add_f32 v[32:33], v[40:41], v[48:49] op_sel_hi:[1,0] neg_lo:[0,1] neg_hi:[0,1]
	v_add_f32_e32 v16, v18, v53
	v_add_f32_e32 v16, v19, v16
	v_pk_mul_f32 v[18:19], v[32:33], v[32:33]
	v_pk_add_f32 v[28:29], v[42:43], v[48:49] op_sel_hi:[1,0] neg_lo:[0,1] neg_hi:[0,1]
	v_add_f32_e32 v16, v18, v16
	v_add_f32_e32 v16, v19, v16
	v_pk_mul_f32 v[18:19], v[28:29], v[28:29]
	v_pk_add_f32 v[24:25], v[44:45], v[48:49] op_sel_hi:[1,0] neg_lo:[0,1] neg_hi:[0,1]
	v_add_f32_e32 v16, v18, v16
	v_add_f32_e32 v16, v19, v16
	v_pk_mul_f32 v[18:19], v[24:25], v[24:25]
	s_waitcnt vmcnt(0)
	v_lshlrev_b32_e32 v40, 16, v12
	v_add_f32_e32 v16, v18, v16
	v_add_f32_e32 v16, v19, v16
	v_pk_add_f32 v[18:19], v[46:47], v[48:49] op_sel_hi:[1,0] neg_lo:[0,1] neg_hi:[0,1]
	v_and_b32_e32 v12, 0xffff0000, v12
	v_pk_mul_f32 v[20:21], v[18:19], v[18:19]
	v_mul_f32_e32 v44, 0xbfb8aa3b, v40
	v_add_f32_e32 v16, v20, v16
	v_add_f32_e32 v16, v21, v16
	ds_bpermute_b32 v20, v49, v16
	v_mul_f32_e32 v45, 0xbfb8aa3b, v12
	v_exp_f32_e32 v44, v44
	v_exp_f32_e32 v45, v45
	v_lshlrev_b32_e32 v41, 16, v13
	s_waitcnt lgkmcnt(0)
	v_add_f32_e32 v16, v16, v20
	v_fmamk_f32 v16, v16, 0x3c800000, v219
	v_cmp_gt_f32_e32 vcc, s36, v16
	v_mul_f32_e32 v20, 0x4b800000, v16
	v_add_f32_e32 v44, 1.0, v44
	v_cndmask_b32_e32 v16, v16, v20, vcc
	v_rsq_f32_e32 v16, v16
	v_add_f32_e32 v45, 1.0, v45
	v_rcp_f32_e32 v44, v44
	v_rcp_f32_e32 v45, v45
	v_mul_f32_e32 v20, 0x45800000, v16
	v_cndmask_b32_e32 v16, v16, v20, vcc
	v_and_b32_e32 v13, 0xffff0000, v13
	v_mul_f32_e32 v40, v44, v40
	v_mul_f32_e32 v44, v52, v16
	v_mul_f32_e32 v12, v45, v12
	v_mul_f32_e32 v45, 0xbfb8aa3b, v41
	v_mul_f32_e32 v12, v12, v44
	v_mul_f32_e32 v44, 0xbfb8aa3b, v13
	v_exp_f32_e32 v45, v45
	v_exp_f32_e32 v44, v44
	v_lshlrev_b32_e32 v42, 16, v14
	v_and_b32_e32 v14, 0xffff0000, v14
	v_add_f32_e32 v45, 1.0, v45
	v_add_f32_e32 v44, 1.0, v44
	v_rcp_f32_e32 v45, v45
	v_rcp_f32_e32 v44, v44
	v_mul_f32_e32 v38, v38, v16
	v_mul_f32_e32 v39, v39, v16
	v_mul_f32_e32 v41, v45, v41
	v_mul_f32_e32 v13, v44, v13
	v_mul_f32_e32 v38, v41, v38
	v_mul_f32_e32 v41, 0xbfb8aa3b, v42
	v_mul_f32_e32 v13, v13, v39
	v_mul_f32_e32 v39, 0xbfb8aa3b, v14
	v_exp_f32_e32 v41, v41
	v_exp_f32_e32 v39, v39
	v_lshlrev_b32_e32 v43, 16, v15
	v_and_b32_e32 v15, 0xffff0000, v15
	v_add_f32_e32 v41, 1.0, v41
	v_add_f32_e32 v39, 1.0, v39
	v_rcp_f32_e32 v41, v41
	v_rcp_f32_e32 v39, v39
	v_lshlrev_b64 v[20:21], 11, v[96:97]
	v_lshl_add_u64 v[20:21], s[52:53], 0, v[20:21]
	v_mul_f32_e32 v41, v41, v42
	v_mul_f32_e32 v42, v55, v16
	v_mul_f32_e32 v14, v39, v14
	v_mul_f32_e32 v14, v14, v42
	v_mul_f32_e32 v42, 0xbfb8aa3b, v15
	v_mul_f32_e32 v39, 0xbfb8aa3b, v43
	v_exp_f32_e32 v42, v42
	v_exp_f32_e32 v39, v39
	v_lshl_add_u64 v[20:21], v[20:21], 0, s[88:89]
	v_mul_f32_e32 v46, v51, v16
	v_add_f32_e32 v42, 1.0, v42
	v_add_f32_e32 v39, 1.0, v39
	v_rcp_f32_e32 v42, v42
	v_rcp_f32_e32 v39, v39
	v_mul_f32_e32 v35, v35, v16
	v_lshl_add_u64 v[20:21], v[20:21], 0, v[184:185]
	v_mul_f32_e32 v15, v42, v15
	v_mul_f32_e32 v40, v40, v46
	v_mul_f32_e32 v44, v54, v16
	v_mul_f32_e32 v34, v34, v16
	v_mul_f32_e32 v39, v39, v43
	v_mul_f32_e32 v15, v15, v35
	v_cvt_pk_bf16_f32 v12, v40, v12
	v_mul_f32_e32 v41, v41, v44
	v_mul_f32_e32 v34, v39, v34
	v_cvt_pk_bf16_f32 v13, v38, v13
	v_cvt_pk_bf16_f32 v14, v41, v14
	v_cvt_pk_bf16_f32 v15, v34, v15
	global_store_dwordx4 v[20:21], v[12:15], off
	v_mul_f32_e32 v30, v30, v16
	v_mul_f32_e32 v26, v26, v16
	v_lshlrev_b32_e32 v12, 16, v8
	v_and_b32_e32 v8, 0xffff0000, v8
	v_mul_f32_e32 v34, 0xbfb8aa3b, v12
	v_mul_f32_e32 v35, 0xbfb8aa3b, v8
	v_exp_f32_e32 v34, v34
	v_exp_f32_e32 v35, v35
	v_lshlrev_b32_e32 v13, 16, v9
	v_and_b32_e32 v9, 0xffff0000, v9
	v_add_f32_e32 v34, 1.0, v34
	v_add_f32_e32 v35, 1.0, v35
	v_rcp_f32_e32 v34, v34
	v_rcp_f32_e32 v35, v35
	v_lshlrev_b32_e32 v14, 16, v10
	v_and_b32_e32 v10, 0xffff0000, v10
	v_mul_f32_e32 v12, v34, v12
	v_mul_f32_e32 v34, v57, v16
	v_mul_f32_e32 v8, v35, v8
	v_mul_f32_e32 v35, 0xbfb8aa3b, v13
	v_exp_f32_e32 v35, v35
	v_mul_f32_e32 v8, v8, v34
	v_mul_f32_e32 v34, 0xbfb8aa3b, v9
	v_exp_f32_e32 v34, v34
	v_add_f32_e32 v35, 1.0, v35
	v_rcp_f32_e32 v35, v35
	v_lshlrev_b32_e32 v15, 16, v11
	v_add_f32_e32 v34, 1.0, v34
	v_rcp_f32_e32 v34, v34
	v_mul_f32_e32 v13, v35, v13
	v_mul_f32_e32 v13, v13, v30
	v_mul_f32_e32 v30, v31, v16
	v_mul_f32_e32 v9, v34, v9
	v_mul_f32_e32 v31, 0xbfb8aa3b, v14
	v_mul_f32_e32 v9, v9, v30
	v_mul_f32_e32 v30, 0xbfb8aa3b, v10
	v_exp_f32_e32 v31, v31
	v_exp_f32_e32 v30, v30
	v_and_b32_e32 v11, 0xffff0000, v11
	v_mul_f32_e32 v38, v56, v16
	v_add_f32_e32 v31, 1.0, v31
	v_add_f32_e32 v30, 1.0, v30
	v_rcp_f32_e32 v31, v31
	v_rcp_f32_e32 v30, v30
	v_mul_f32_e32 v12, v12, v38
	v_mul_f32_e32 v34, v58, v16
	v_mul_f32_e32 v14, v31, v14
	v_mul_f32_e32 v31, v59, v16
	v_mul_f32_e32 v10, v30, v10
	v_mul_f32_e32 v30, 0xbfb8aa3b, v15
	v_exp_f32_e32 v30, v30
	v_mul_f32_e32 v10, v10, v31
	v_mul_f32_e32 v31, 0xbfb8aa3b, v11
	v_exp_f32_e32 v31, v31
	v_add_f32_e32 v30, 1.0, v30
	v_rcp_f32_e32 v30, v30
	v_cvt_pk_bf16_f32 v8, v12, v8
	v_add_f32_e32 v31, 1.0, v31
	v_rcp_f32_e32 v31, v31
	v_mul_f32_e32 v15, v30, v15
	v_mul_f32_e32 v15, v15, v26
	v_mul_f32_e32 v26, v27, v16
	v_mul_f32_e32 v11, v31, v11
	v_mul_f32_e32 v11, v11, v26
	v_mul_f32_e32 v14, v14, v34
	v_cvt_pk_bf16_f32 v9, v13, v9
	v_cvt_pk_bf16_f32 v10, v14, v10
	v_cvt_pk_bf16_f32 v11, v15, v11
	global_store_dwordx4 v[20:21], v[8:11], off offset:16
	v_mul_f32_e32 v14, v60, v16
	s_nop 0
	v_lshlrev_b32_e32 v8, 16, v4
	v_and_b32_e32 v4, 0xffff0000, v4
	v_mul_f32_e32 v12, 0xbfb8aa3b, v8
	v_mul_f32_e32 v13, 0xbfb8aa3b, v4
	v_exp_f32_e32 v12, v12
	v_exp_f32_e32 v13, v13
	v_lshlrev_b32_e32 v9, 16, v5
	v_and_b32_e32 v5, 0xffff0000, v5
	v_add_f32_e32 v12, 1.0, v12
	v_add_f32_e32 v13, 1.0, v13
	v_rcp_f32_e32 v12, v12
	v_rcp_f32_e32 v13, v13
	v_lshlrev_b32_e32 v10, 16, v6
	v_and_b32_e32 v6, 0xffff0000, v6
	v_mul_f32_e32 v8, v12, v8
	v_mul_f32_e32 v12, v61, v16
	v_mul_f32_e32 v4, v13, v4
	v_mul_f32_e32 v13, 0xbfb8aa3b, v9
	v_mul_f32_e32 v4, v4, v12
	v_mul_f32_e32 v12, 0xbfb8aa3b, v5
	v_exp_f32_e32 v13, v13
	v_exp_f32_e32 v12, v12
	v_lshlrev_b32_e32 v11, 16, v7
	v_and_b32_e32 v7, 0xffff0000, v7
	v_add_f32_e32 v13, 1.0, v13
	v_add_f32_e32 v12, 1.0, v12
	v_rcp_f32_e32 v13, v13
	v_rcp_f32_e32 v12, v12
	v_mul_f32_e32 v8, v8, v14
	v_mul_f32_e32 v14, v22, v16
	v_mul_f32_e32 v9, v13, v9
	v_mul_f32_e32 v13, v23, v16
	v_mul_f32_e32 v5, v12, v5
	v_mul_f32_e32 v12, 0xbfb8aa3b, v10
	v_mul_f32_e32 v5, v5, v13
	v_mul_f32_e32 v13, 0xbfb8aa3b, v6
	v_exp_f32_e32 v12, v12
	v_exp_f32_e32 v13, v13
	v_mul_f32_e32 v9, v9, v14
	v_mul_f32_e32 v14, v62, v16
	v_add_f32_e32 v12, 1.0, v12
	v_add_f32_e32 v13, 1.0, v13
	v_rcp_f32_e32 v12, v12
	v_rcp_f32_e32 v13, v13
	v_cvt_pk_bf16_f32 v4, v8, v4
	v_cvt_pk_bf16_f32 v5, v9, v5
	v_mul_f32_e32 v10, v12, v10
	v_mul_f32_e32 v12, v17, v16
	v_mul_f32_e32 v6, v13, v6
	v_mul_f32_e32 v13, 0xbfb8aa3b, v11
	v_mul_f32_e32 v6, v6, v12
	v_mul_f32_e32 v12, 0xbfb8aa3b, v7
	v_exp_f32_e32 v13, v13
	v_exp_f32_e32 v12, v12
	v_mul_f32_e32 v10, v10, v14
	v_mul_f32_e32 v14, v36, v16
	v_add_f32_e32 v13, 1.0, v13
	v_add_f32_e32 v12, 1.0, v12
	v_rcp_f32_e32 v13, v13
	v_rcp_f32_e32 v12, v12
	v_cvt_pk_bf16_f32 v6, v10, v6
	v_mul_f32_e32 v10, v32, v16
	v_mul_f32_e32 v11, v13, v11
	v_mul_f32_e32 v13, v37, v16
	v_mul_f32_e32 v7, v12, v7
	v_mul_f32_e32 v7, v7, v13
	v_mul_f32_e32 v11, v11, v14
	v_cvt_pk_bf16_f32 v7, v11, v7
	global_store_dwordx4 v[20:21], v[4:7], off offset:32
	s_nop 1
	v_lshlrev_b32_e32 v4, 16, v0
	v_and_b32_e32 v0, 0xffff0000, v0
	v_mul_f32_e32 v8, 0xbfb8aa3b, v4
	v_mul_f32_e32 v9, 0xbfb8aa3b, v0
	v_exp_f32_e32 v8, v8
	v_exp_f32_e32 v9, v9
	v_lshlrev_b32_e32 v5, 16, v1
	v_and_b32_e32 v1, 0xffff0000, v1
	v_add_f32_e32 v8, 1.0, v8
	v_add_f32_e32 v9, 1.0, v9
	v_rcp_f32_e32 v8, v8
	v_rcp_f32_e32 v9, v9
	v_lshlrev_b32_e32 v6, 16, v2
	v_and_b32_e32 v2, 0xffff0000, v2
	v_mul_f32_e32 v4, v8, v4
	v_mul_f32_e32 v8, v33, v16
	v_mul_f32_e32 v0, v9, v0
	v_mul_f32_e32 v9, 0xbfb8aa3b, v5
	v_mul_f32_e32 v0, v0, v8
	v_mul_f32_e32 v8, 0xbfb8aa3b, v1
	v_exp_f32_e32 v9, v9
	v_exp_f32_e32 v8, v8
	v_lshlrev_b32_e32 v7, 16, v3
	v_and_b32_e32 v3, 0xffff0000, v3
	v_add_f32_e32 v9, 1.0, v9
	v_add_f32_e32 v8, 1.0, v8
	v_rcp_f32_e32 v9, v9
	v_rcp_f32_e32 v8, v8
	v_mul_f32_e32 v4, v4, v10
	v_mul_f32_e32 v10, v28, v16
	v_mul_f32_e32 v5, v9, v5
	v_mul_f32_e32 v9, v29, v16
	v_mul_f32_e32 v1, v8, v1
	v_mul_f32_e32 v8, 0xbfb8aa3b, v6
	v_mul_f32_e32 v1, v1, v9
	v_mul_f32_e32 v9, 0xbfb8aa3b, v2
	v_exp_f32_e32 v8, v8
	v_exp_f32_e32 v9, v9
	v_mul_f32_e32 v5, v5, v10
	v_mul_f32_e32 v10, v24, v16
	v_add_f32_e32 v8, 1.0, v8
	v_add_f32_e32 v9, 1.0, v9
	v_rcp_f32_e32 v8, v8
	v_rcp_f32_e32 v9, v9
	v_cvt_pk_bf16_f32 v0, v4, v0
	v_cvt_pk_bf16_f32 v1, v5, v1
	v_mul_f32_e32 v6, v8, v6
	v_mul_f32_e32 v8, v25, v16
	v_mul_f32_e32 v2, v9, v2
	v_mul_f32_e32 v9, 0xbfb8aa3b, v7
	v_mul_f32_e32 v2, v2, v8
	v_mul_f32_e32 v8, 0xbfb8aa3b, v3
	v_exp_f32_e32 v9, v9
	v_exp_f32_e32 v8, v8
	v_mul_f32_e32 v6, v6, v10
	v_mul_f32_e32 v10, v18, v16
	v_add_f32_e32 v9, 1.0, v9
	v_add_f32_e32 v8, 1.0, v8
	v_rcp_f32_e32 v9, v9
	v_rcp_f32_e32 v8, v8
	v_cvt_pk_bf16_f32 v2, v6, v2
	v_mul_f32_e32 v7, v9, v7
	v_mul_f32_e32 v9, v19, v16
	v_mul_f32_e32 v3, v8, v3
	v_mul_f32_e32 v3, v3, v9
	v_mul_f32_e32 v7, v7, v10
	v_cvt_pk_bf16_f32 v3, v7, v3
	global_store_dwordx4 v[20:21], v[0:3], off offset:48
	s_barrier
	s_load_dword s20, s[4:5], 0x0
	s_waitcnt lgkmcnt(0)
	s_lshl_b32 s20, s20, 1
	s_add_i32 s38, s20, s38
	s_cmp_ge_i32 s38, s30
	s_cbranch_scc1 .LBB0_202

.LBB0_256:
	s_waitcnt vmcnt(0)
	v_mul_f32_e32 v0, 0xbfb8aa3b, v62
	v_rndne_f32_e32 v1, v0
	s_mov_b32 s0, 0xbfb8aa3b
	v_sub_f32_e32 v2, v0, v1
	v_fma_f32 v0, v62, s0, -v0
	v_fmac_f32_e32 v0, 0xb2a5705f, v62
	v_add_f32_e32 v0, v2, v0
	v_cvt_i32_f32_e32 v1, v1
	v_exp_f32_e32 v0, v0
	s_mov_b32 s1, 0x42ce8ed0
	v_cmp_nlt_f32_e32 vcc, s1, v62
	s_mov_b32 s6, 0x3f2aaaab
	v_ldexp_f32 v0, v0, v1
	v_cndmask_b32_e32 v0, 0, v0, vcc
	v_cmp_ngt_f32_e32 vcc, s3, v62
	s_mov_b32 s7, 0x3f317218
	s_mov_b32 s8, 0x33800000
	v_cndmask_b32_e32 v2, v238, v0, vcc
	v_add_f32_e32 v3, 1.0, v2
	v_cvt_f64_f32_e32 v[0:1], v3
	v_frexp_exp_i32_f64_e32 v0, v[0:1]
	v_frexp_mant_f32_e32 v1, v3
	v_cmp_gt_f32_e32 vcc, s6, v1
	v_add_f32_e32 v21, -1.0, v3
	v_sub_f32_e32 v29, v2, v21
	v_subbrev_co_u32_e32 v0, vcc, 0, v0, vcc
	v_cvt_f32_i32_e32 v1, v0
	v_sub_u32_e32 v0, 0, v0
	v_ldexp_f32 v6, v3, v0
	v_sub_f32_e32 v3, v21, v3
	v_add_f32_e32 v3, 1.0, v3
	v_add_f32_e32 v21, 1.0, v6
	v_add_f32_e32 v3, v29, v3
	v_add_f32_e32 v29, -1.0, v21
	v_ldexp_f32 v0, v3, v0
	v_sub_f32_e32 v29, v6, v29
	v_add_f32_e32 v29, v0, v29
	v_add_f32_e32 v7, -1.0, v6
	v_add_f32_e32 v44, v21, v29
	v_add_f32_e32 v3, 1.0, v7
	v_rcp_f32_e32 v45, v44
	v_sub_f32_e32 v3, v6, v3
	v_add_f32_e32 v0, v0, v3
	v_add_f32_e32 v3, v7, v0
	v_mul_f32_e32 v6, v3, v45
	v_mul_f32_e32 v46, v44, v6
	v_sub_f32_e32 v21, v21, v44
	v_add_f32_e32 v21, v29, v21
	v_fma_f32 v29, v6, v44, -v46
	v_fmac_f32_e32 v29, v6, v21
	v_add_f32_e32 v47, v46, v29
	v_sub_f32_e32 v48, v3, v47
	v_sub_f32_e32 v7, v7, v3
	v_sub_f32_e32 v3, v3, v48
	v_sub_f32_e32 v46, v47, v46
	v_add_f32_e32 v0, v0, v7
	v_sub_f32_e32 v3, v3, v47
	v_sub_f32_e32 v29, v46, v29
	v_add_f32_e32 v0, v0, v3
	v_add_f32_e32 v0, v29, v0
	v_add_f32_e32 v3, v48, v0
	v_mul_f32_e32 v7, v45, v3
	v_mul_f32_e32 v46, v44, v7
	v_add_f32_e32 v29, v6, v7
	v_fma_f32 v44, v7, v44, -v46
	v_sub_f32_e32 v6, v29, v6
	v_fmac_f32_e32 v44, v7, v21
	v_sub_f32_e32 v6, v7, v6
	v_add_f32_e32 v7, v46, v44
	v_sub_f32_e32 v21, v3, v7
	v_sub_f32_e32 v46, v7, v46
	v_sub_f32_e32 v44, v46, v44
	v_sub_f32_e32 v46, v48, v3
	v_sub_f32_e32 v3, v3, v21
	v_add_f32_e32 v0, v0, v46
	v_sub_f32_e32 v3, v3, v7
	v_add_f32_e32 v0, v0, v3
	v_add_f32_e32 v0, v44, v0
	v_add_f32_e32 v0, v21, v0
	v_mul_f32_e32 v0, v45, v0
	v_add_f32_e32 v0, v6, v0
	v_add_f32_e32 v3, v29, v0
	v_mul_f32_e32 v7, v3, v3
	v_fmamk_f32 v44, v7, 0x3e9b6dac, v222
	v_mul_f32_e32 v21, v3, v7
	v_fmaak_f32 v7, v7, v44, 0x3f2aaada
	v_ldexp_f32 v6, v3, 1
	v_mul_f32_e32 v7, v21, v7
	v_add_f32_e32 v21, v6, v7
	v_sub_f32_e32 v3, v3, v29
	v_mul_f32_e32 v4, 0x3f317218, v1
	v_sub_f32_e32 v0, v0, v3
	v_sub_f32_e32 v3, v21, v6
	v_fma_f32 v5, v1, s7, -v4
	v_ldexp_f32 v0, v0, 1
	v_sub_f32_e32 v3, v7, v3
	v_fmac_f32_e32 v5, 0xb102e308, v1
	v_add_f32_e32 v0, v0, v3
	v_add_f32_e32 v1, v4, v5
	v_add_f32_e32 v3, v21, v0
	v_add_f32_e32 v6, v1, v3
	v_sub_f32_e32 v4, v1, v4
	v_sub_f32_e32 v4, v5, v4
	v_sub_f32_e32 v5, v3, v21
	v_sub_f32_e32 v7, v6, v1
	v_sub_f32_e32 v0, v0, v5
	v_sub_f32_e32 v3, v3, v7
	v_sub_f32_e32 v7, v6, v7
	v_add_f32_e32 v5, v4, v0
	v_sub_f32_e32 v1, v1, v7
	v_add_f32_e32 v1, v3, v1
	v_sub_f32_e32 v7, v5, v4
	v_add_f32_e32 v1, v5, v1
	v_sub_f32_e32 v5, v5, v7
	v_add_f32_e32 v3, v6, v1
	v_sub_f32_e32 v0, v0, v7
	v_sub_f32_e32 v4, v4, v5
	v_mul_f32_e32 v5, 0xbfb8aa3b, v61
	v_add_f32_e32 v0, v0, v4
	v_sub_f32_e32 v4, v3, v6
	v_rndne_f32_e32 v6, v5
	v_sub_f32_e32 v7, v5, v6
	v_fma_f32 v5, v61, s0, -v5
	v_fmac_f32_e32 v5, 0xb2a5705f, v61
	v_add_f32_e32 v5, v7, v5
	v_exp_f32_e32 v5, v5
	v_cvt_i32_f32_e32 v6, v6
	v_sub_f32_e32 v1, v1, v4
	v_add_f32_e32 v0, v0, v1
	v_add_f32_e32 v3, v3, v0
	v_ldexp_f32 v0, v5, v6
	v_cmp_nlt_f32_e64 s[0:1], s1, v61
	v_cmp_lt_f32_e64 vcc, |v2|, s8
	v_and_b32_e32 v56, 48, v58
	v_cndmask_b32_e64 v0, 0, v0, s[0:1]
	v_cmp_ngt_f32_e64 s[0:1], s3, v61
	s_nop 1
	v_cndmask_b32_e64 v4, v238, v0, s[0:1]
	v_add_f32_e32 v5, 1.0, v4
	v_cvt_f64_f32_e32 v[0:1], v5
	v_frexp_exp_i32_f64_e32 v0, v[0:1]
	v_frexp_mant_f32_e32 v1, v5
	v_cmp_gt_f32_e64 s[0:1], s6, v1
	v_add_f32_e32 v44, -1.0, v5
	v_sub_f32_e32 v45, v4, v44
	v_subbrev_co_u32_e64 v0, s[0:1], 0, v0, s[0:1]
	v_cvt_f32_i32_e32 v1, v0
	v_sub_u32_e32 v0, 0, v0
	v_ldexp_f32 v21, v5, v0
	v_sub_f32_e32 v5, v44, v5
	v_add_f32_e32 v5, 1.0, v5
	v_add_f32_e32 v44, 1.0, v21
	v_add_f32_e32 v5, v45, v5
	v_add_f32_e32 v45, -1.0, v44
	v_ldexp_f32 v0, v5, v0
	v_sub_f32_e32 v45, v21, v45
	v_add_f32_e32 v45, v0, v45
	v_add_f32_e32 v29, -1.0, v21
	v_add_f32_e32 v46, v44, v45
	v_add_f32_e32 v5, 1.0, v29
	v_rcp_f32_e32 v47, v46
	v_sub_f32_e32 v5, v21, v5
	v_add_f32_e32 v0, v0, v5
	v_add_f32_e32 v5, v29, v0
	v_mul_f32_e32 v21, v5, v47
	v_mul_f32_e32 v48, v46, v21
	v_sub_f32_e32 v44, v44, v46
	v_add_f32_e32 v44, v45, v44
	v_fma_f32 v45, v21, v46, -v48
	v_fmac_f32_e32 v45, v21, v44
	v_add_f32_e32 v49, v48, v45
	v_sub_f32_e32 v50, v5, v49
	v_sub_f32_e32 v29, v29, v5
	v_sub_f32_e32 v5, v5, v50
	v_sub_f32_e32 v48, v49, v48
	v_add_f32_e32 v0, v0, v29
	v_sub_f32_e32 v5, v5, v49
	v_sub_f32_e32 v45, v48, v45
	v_add_f32_e32 v0, v0, v5
	v_add_f32_e32 v0, v45, v0
	v_add_f32_e32 v5, v50, v0
	v_mul_f32_e32 v29, v47, v5
	v_mul_f32_e32 v48, v46, v29
	v_add_f32_e32 v45, v21, v29
	v_fma_f32 v46, v29, v46, -v48
	v_sub_f32_e32 v21, v45, v21
	v_fmac_f32_e32 v46, v29, v44
	v_sub_f32_e32 v21, v29, v21
	v_add_f32_e32 v29, v48, v46
	v_sub_f32_e32 v44, v5, v29
	v_sub_f32_e32 v48, v29, v48
	v_sub_f32_e32 v46, v48, v46
	v_sub_f32_e32 v48, v50, v5
	v_sub_f32_e32 v5, v5, v44
	v_add_f32_e32 v0, v0, v48
	v_sub_f32_e32 v5, v5, v29
	v_add_f32_e32 v0, v0, v5
	v_add_f32_e32 v0, v46, v0
	v_add_f32_e32 v0, v44, v0
	v_mul_f32_e32 v0, v47, v0
	v_add_f32_e32 v0, v21, v0
	v_add_f32_e32 v5, v45, v0
	v_mul_f32_e32 v29, v5, v5
	v_fmamk_f32 v46, v29, 0x3e9b6dac, v222
	v_mul_f32_e32 v44, v5, v29
	v_fmaak_f32 v29, v29, v46, 0x3f2aaada
	v_ldexp_f32 v21, v5, 1
	v_mul_f32_e32 v29, v44, v29
	v_add_f32_e32 v44, v21, v29
	v_sub_f32_e32 v5, v5, v45
	v_mul_f32_e32 v6, 0x3f317218, v1
	v_sub_f32_e32 v0, v0, v5
	v_sub_f32_e32 v5, v44, v21
	v_fma_f32 v7, v1, s7, -v6
	v_ldexp_f32 v0, v0, 1
	v_sub_f32_e32 v5, v29, v5
	v_fmac_f32_e32 v7, 0xb102e308, v1
	v_add_f32_e32 v0, v0, v5
	v_add_f32_e32 v1, v6, v7
	v_add_f32_e32 v5, v44, v0
	v_add_f32_e32 v21, v1, v5
	v_sub_f32_e32 v6, v1, v6
	v_sub_f32_e32 v6, v7, v6
	v_sub_f32_e32 v7, v5, v44
	v_sub_f32_e32 v29, v21, v1
	v_sub_f32_e32 v0, v0, v7
	v_sub_f32_e32 v5, v5, v29
	v_sub_f32_e32 v29, v21, v29
	v_add_f32_e32 v7, v6, v0
	v_sub_f32_e32 v1, v1, v29
	v_add_f32_e32 v1, v5, v1
	v_sub_f32_e32 v29, v7, v6
	v_add_f32_e32 v1, v7, v1
	v_sub_f32_e32 v7, v7, v29
	v_add_f32_e32 v5, v21, v1
	v_sub_f32_e32 v0, v0, v29
	v_sub_f32_e32 v6, v6, v7
	v_add_f32_e32 v0, v0, v6
	v_sub_f32_e32 v6, v5, v21
	v_sub_f32_e32 v1, v1, v6
	v_add_f32_e32 v0, v0, v1
	v_sub_u32_e32 v1, 0x7f, v59
	v_cvt_f32_i32_e32 v1, v1
	v_cmp_neq_f32_e64 s[0:1], s21, v2
	v_add_f32_e32 v0, v5, v0
	v_cmp_neq_f32_e64 s[36:37], s21, v4
	v_cndmask_b32_e64 v3, v238, v3, s[0:1]
	v_cmp_lt_f32_e64 s[0:1], |v4|, s8
	v_cndmask_b32_e64 v0, v238, v0, s[36:37]
	v_cndmask_b32_e32 v2, v3, v2, vcc
	v_cndmask_b32_e64 v0, v0, v4, s[0:1]
	v_mul_f32_e64 v1, v1, -v0
	v_mul_f32_e32 v0, 0x3fb8aa3b, v1
	s_mov_b32 s0, 0x3fb8aa3b
	v_fma_f32 v4, v1, s0, -v0
	v_rndne_f32_e32 v5, v0
	v_fmac_f32_e32 v4, 0x32a5705f, v1
	v_sub_f32_e32 v0, v0, v5
	v_cvt_f32_i32_e32 v3, v59
	v_add_f32_e32 v0, v0, v4
	v_exp_f32_e32 v4, v0
	v_cvt_i32_f32_e32 v5, v5
	v_mul_f32_e64 v2, v3, -v2
	v_mul_f32_e32 v3, 0x3fb8aa3b, v2
	v_rndne_f32_e32 v6, v3
	v_ldexp_f32 v4, v4, v5
	v_fma_f32 v5, v2, s0, -v3
	v_fmac_f32_e32 v5, 0x32a5705f, v2
	v_sub_f32_e32 v3, v3, v6
	v_add_f32_e32 v3, v3, v5
	v_exp_f32_e32 v3, v3
	v_cvt_i32_f32_e32 v5, v6
	s_mov_b32 s1, 0xc2ce8ed0
	v_cmp_ngt_f32_e32 vcc, s1, v1
	s_mov_b32 s0, 0x42b17218
	v_lshlrev_b32_e32 v6, 1, v59
	v_cndmask_b32_e32 v4, 0, v4, vcc
	v_cmp_nlt_f32_e32 vcc, s0, v1
	v_ldexp_f32 v1, v3, v5
	v_and_b32_e32 v0, 15, v58
	v_cndmask_b32_e32 v21, v238, v4, vcc
	v_cmp_ngt_f32_e32 vcc, s1, v2
	v_mul_u32_u24_e32 v4, 0x1100, v60
	v_lshlrev_b32_e32 v4, 1, v4
	v_cndmask_b32_e32 v1, 0, v1, vcc
	v_cmp_nlt_f32_e32 vcc, s0, v2
	s_movk_i32 s0, 0x1100
	s_nop 0
	v_cndmask_b32_e32 v3, v238, v1, vcc
	v_mul_f32_e32 v1, v21, v42
	v_cvt_pk_bf16_f32 v2, v1, v1
	v_mad_u32_u24 v1, v60, s0, v59
	v_lshl_add_u32 v1, v1, 1, s20
	ds_write_b16_d16_hi v1, v2
	v_mul_f32_e32 v2, v3, v42
	v_cvt_pk_bf16_f32 v5, v2, v2
	v_add3_u32 v2, s20, v6, v4
	ds_write_b16_d16_hi v2, v5 offset:17408
	v_mul_f32_e32 v5, v21, v43
	v_cvt_pk_bf16_f32 v5, v5, v5
	v_add3_u32 v42, s20, v4, v6
	v_mul_f32_e32 v4, v3, v43
	ds_write_b16_d16_hi v42, v5 offset:272
	v_cvt_pk_bf16_f32 v4, v4, v4
	ds_write_b16_d16_hi v2, v4 offset:17680
	v_mul_f32_e32 v4, v21, v40
	v_cvt_pk_bf16_f32 v4, v4, v4
	ds_write_b16_d16_hi v1, v4 offset:544
	v_mul_f32_e32 v4, v3, v40
	v_cvt_pk_bf16_f32 v4, v4, v4
	ds_write_b16_d16_hi v2, v4 offset:17952
	v_mul_f32_e32 v4, v21, v41
	v_cvt_pk_bf16_f32 v4, v4, v4
	ds_write_b16_d16_hi v42, v4 offset:816
	v_mul_f32_e32 v4, v3, v41
	v_cvt_pk_bf16_f32 v4, v4, v4
	ds_write_b16_d16_hi v2, v4 offset:18224
	v_mul_f32_e32 v4, v21, v38
	v_cvt_pk_bf16_f32 v4, v4, v4
	ds_write_b16_d16_hi v1, v4 offset:1088
	v_mul_f32_e32 v4, v3, v38
	v_cvt_pk_bf16_f32 v4, v4, v4
	ds_write_b16_d16_hi v2, v4 offset:18496
	v_mul_f32_e32 v4, v21, v39
	v_cvt_pk_bf16_f32 v4, v4, v4
	ds_write_b16_d16_hi v42, v4 offset:1360
	v_mul_f32_e32 v4, v3, v39
	v_cvt_pk_bf16_f32 v4, v4, v4
	ds_write_b16_d16_hi v2, v4 offset:18768
	v_mul_f32_e32 v4, v21, v36
	v_cvt_pk_bf16_f32 v4, v4, v4
	ds_write_b16_d16_hi v1, v4 offset:1632
	v_mul_f32_e32 v4, v3, v36
	v_cvt_pk_bf16_f32 v4, v4, v4
	ds_write_b16_d16_hi v2, v4 offset:19040
	v_mul_f32_e32 v4, v21, v37
	v_cvt_pk_bf16_f32 v4, v4, v4
	ds_write_b16_d16_hi v42, v4 offset:1904
	v_mul_f32_e32 v4, v3, v37
	v_cvt_pk_bf16_f32 v4, v4, v4
	ds_write_b16_d16_hi v2, v4 offset:19312
	v_mul_f32_e32 v4, v21, v34
	v_cvt_pk_bf16_f32 v4, v4, v4
	ds_write_b16_d16_hi v1, v4 offset:2176
	v_mul_f32_e32 v4, v3, v34
	v_cvt_pk_bf16_f32 v4, v4, v4
	ds_write_b16_d16_hi v2, v4 offset:19584
	v_mul_f32_e32 v4, v21, v35
	v_cvt_pk_bf16_f32 v4, v4, v4
	ds_write_b16_d16_hi v42, v4 offset:2448
	v_mul_f32_e32 v4, v3, v35
	v_cvt_pk_bf16_f32 v4, v4, v4
	ds_write_b16_d16_hi v2, v4 offset:19856
	v_mul_f32_e32 v4, v21, v32
	v_cvt_pk_bf16_f32 v4, v4, v4
	ds_write_b16_d16_hi v1, v4 offset:2720
	v_mul_f32_e32 v4, v3, v32
	v_cvt_pk_bf16_f32 v4, v4, v4
	ds_write_b16_d16_hi v2, v4 offset:20128
	v_mul_f32_e32 v4, v21, v33
	v_cvt_pk_bf16_f32 v4, v4, v4
	ds_write_b16_d16_hi v42, v4 offset:2992
	v_mul_f32_e32 v4, v3, v33
	v_cvt_pk_bf16_f32 v4, v4, v4
	ds_write_b16_d16_hi v2, v4 offset:20400
	v_mul_f32_e32 v4, v21, v30
	v_cvt_pk_bf16_f32 v4, v4, v4
	ds_write_b16_d16_hi v1, v4 offset:3264
	v_mul_f32_e32 v4, v3, v30
	v_cvt_pk_bf16_f32 v4, v4, v4
	ds_write_b16_d16_hi v2, v4 offset:20672
	v_mul_f32_e32 v4, v21, v31
	v_cvt_pk_bf16_f32 v4, v4, v4
	ds_write_b16_d16_hi v42, v4 offset:3536
	v_mul_f32_e32 v4, v3, v31
	v_cvt_pk_bf16_f32 v4, v4, v4
	ds_write_b16_d16_hi v2, v4 offset:20944
	v_mul_f32_e32 v4, v21, v28
	v_cvt_pk_bf16_f32 v4, v4, v4
	ds_write_b16_d16_hi v1, v4 offset:3808
	v_mul_f32_e32 v4, v3, v28
	v_cvt_pk_bf16_f32 v4, v4, v4
	ds_write_b16_d16_hi v2, v4 offset:21216
	v_mul_f32_e32 v4, v21, v19
	v_cvt_pk_bf16_f32 v4, v4, v4
	ds_write_b16_d16_hi v42, v4 offset:4080
	v_mul_f32_e32 v4, v3, v19
	v_cvt_pk_bf16_f32 v4, v4, v4
	ds_write_b16_d16_hi v2, v4 offset:21488
	v_mul_f32_e32 v4, v21, v26
	v_cvt_pk_bf16_f32 v4, v4, v4
	ds_write_b16_d16_hi v1, v4 offset:4352
	v_mul_f32_e32 v4, v3, v26
	v_cvt_pk_bf16_f32 v4, v4, v4
	ds_write_b16_d16_hi v2, v4 offset:21760
	v_mul_f32_e32 v4, v21, v27
	v_cvt_pk_bf16_f32 v4, v4, v4
	ds_write_b16_d16_hi v42, v4 offset:4624
	v_mul_f32_e32 v4, v3, v27
	v_cvt_pk_bf16_f32 v4, v4, v4
	ds_write_b16_d16_hi v2, v4 offset:22032
	v_mul_f32_e32 v4, v21, v24
	v_cvt_pk_bf16_f32 v4, v4, v4
	ds_write_b16_d16_hi v1, v4 offset:4896
	v_mul_f32_e32 v4, v3, v24
	v_cvt_pk_bf16_f32 v4, v4, v4
	ds_write_b16_d16_hi v2, v4 offset:22304
	v_mul_f32_e32 v4, v21, v25
	v_cvt_pk_bf16_f32 v4, v4, v4
	ds_write_b16_d16_hi v42, v4 offset:5168
	v_mul_f32_e32 v4, v3, v25
	v_cvt_pk_bf16_f32 v4, v4, v4
	ds_write_b16_d16_hi v2, v4 offset:22576
	v_mul_f32_e32 v4, v21, v22
	v_cvt_pk_bf16_f32 v4, v4, v4
	ds_write_b16_d16_hi v1, v4 offset:5440
	v_mul_f32_e32 v4, v3, v22
	v_cvt_pk_bf16_f32 v4, v4, v4
	ds_write_b16_d16_hi v2, v4 offset:22848
	v_mul_f32_e32 v4, v21, v23
	v_cvt_pk_bf16_f32 v4, v4, v4
	ds_write_b16_d16_hi v42, v4 offset:5712
	v_mul_f32_e32 v4, v3, v23
	v_cvt_pk_bf16_f32 v4, v4, v4
	ds_write_b16_d16_hi v2, v4 offset:23120
	v_mul_f32_e32 v4, v21, v16
	v_cvt_pk_bf16_f32 v4, v4, v4
	ds_write_b16_d16_hi v1, v4 offset:5984
	global_load_dwordx4 v[4:7], v[8:9], off offset:1024
	global_load_dwordx4 v[22:25], v[8:9], off offset:1040
	global_load_dwordx4 v[26:29], v[8:9], off offset:1056
	global_load_dwordx4 v[30:33], v[8:9], off offset:1072
	v_mul_f32_e32 v16, v3, v16
	v_cvt_pk_bf16_f32 v16, v16, v16
	ds_write_b16_d16_hi v2, v16 offset:23392
	v_mul_f32_e32 v16, v21, v17
	v_cvt_pk_bf16_f32 v16, v16, v16
	ds_write_b16_d16_hi v42, v16 offset:6256
	v_mul_f32_e32 v16, v3, v17
	v_cvt_pk_bf16_f32 v16, v16, v16
	ds_write_b16_d16_hi v2, v16 offset:23664
	v_mul_f32_e32 v16, v21, v14
	v_cvt_pk_bf16_f32 v16, v16, v16
	v_mul_f32_e32 v14, v3, v14
	ds_write_b16_d16_hi v1, v16 offset:6528
	v_cvt_pk_bf16_f32 v14, v14, v14
	ds_write_b16_d16_hi v2, v14 offset:23936
	v_mul_f32_e32 v14, v21, v15
	v_cvt_pk_bf16_f32 v8, v14, v14
	ds_write_b16_d16_hi v42, v8 offset:6800
	v_mul_f32_e32 v8, v3, v15
	v_cvt_pk_bf16_f32 v8, v8, v8
	ds_write_b16_d16_hi v2, v8 offset:24208
	v_mul_f32_e32 v8, v21, v12
	v_cvt_pk_bf16_f32 v8, v8, v8
	ds_write_b16_d16_hi v1, v8 offset:7072
	v_mul_f32_e32 v8, v3, v12
	v_cvt_pk_bf16_f32 v8, v8, v8
	ds_write_b16_d16_hi v2, v8 offset:24480
	v_mul_f32_e32 v8, v21, v13
	v_cvt_pk_bf16_f32 v8, v8, v8
	ds_write_b16_d16_hi v42, v8 offset:7344
	v_mul_f32_e32 v8, v3, v13
	v_cvt_pk_bf16_f32 v8, v8, v8
	ds_write_b16_d16_hi v2, v8 offset:24752
	v_mul_f32_e32 v8, v21, v10
	v_cvt_pk_bf16_f32 v8, v8, v8
	ds_write_b16_d16_hi v1, v8 offset:7616
	v_mul_f32_e32 v8, v3, v10
	v_cvt_pk_bf16_f32 v8, v8, v8
	ds_write_b16_d16_hi v2, v8 offset:25024
	v_mul_f32_e32 v8, v21, v11
	v_cvt_pk_bf16_f32 v8, v8, v8
	ds_write_b16_d16_hi v42, v8 offset:7888
	v_mul_f32_e32 v8, v3, v11
	v_cvt_pk_bf16_f32 v8, v8, v8
	ds_write_b16_d16_hi v2, v8 offset:25296
	v_mul_f32_e32 v8, v21, v20
	v_cvt_pk_bf16_f32 v8, v8, v8
	ds_write_b16_d16_hi v1, v8 offset:8160
	v_mul_f32_e32 v8, v3, v20
	v_cvt_pk_bf16_f32 v8, v8, v8
	ds_write_b16_d16_hi v2, v8 offset:25568
	v_mul_f32_e32 v8, v21, v18
	v_cvt_pk_bf16_f32 v8, v8, v8
	v_mul_f32_e32 v3, v3, v18
	ds_write_b16_d16_hi v42, v8 offset:8432
	v_cvt_pk_bf16_f32 v3, v3, v3
	s_mov_b32 s0, 0xfffffe0
	ds_write_b16_d16_hi v2, v3 offset:25840
	s_waitcnt vmcnt(3)
	ds_write_b16 v1, v4 offset:34816
	ds_write_b16_d16_hi v2, v4 offset:35088
	ds_write_b16 v1, v5 offset:35360
	ds_write_b16_d16_hi v2, v5 offset:35632
	ds_write_b16 v1, v6 offset:35904
	ds_write_b16_d16_hi v2, v6 offset:36176
	ds_write_b16 v1, v7 offset:36448
	ds_write_b16_d16_hi v2, v7 offset:36720
	s_waitcnt vmcnt(2)
	ds_write_b16 v1, v22 offset:36992
	ds_write_b16_d16_hi v2, v22 offset:37264
	ds_write_b16 v1, v23 offset:37536
	ds_write_b16_d16_hi v2, v23 offset:37808
	ds_write_b16 v1, v24 offset:38080
	ds_write_b16_d16_hi v2, v24 offset:38352
	ds_write_b16 v1, v25 offset:38624
	ds_write_b16_d16_hi v2, v25 offset:38896
	s_waitcnt vmcnt(1)
	ds_write_b16 v1, v26 offset:39168
	ds_write_b16_d16_hi v2, v26 offset:39440
	ds_write_b16 v1, v27 offset:39712
	ds_write_b16_d16_hi v2, v27 offset:39984
	ds_write_b16 v1, v28 offset:40256
	ds_write_b16_d16_hi v2, v28 offset:40528
	ds_write_b16 v1, v29 offset:40800
	ds_write_b16_d16_hi v2, v29 offset:41072
	s_waitcnt vmcnt(0)
	ds_write_b16 v1, v30 offset:41344
	ds_write_b16_d16_hi v2, v30 offset:41616
	ds_write_b16 v1, v31 offset:41888
	ds_write_b16_d16_hi v2, v31 offset:42160
	ds_write_b16 v1, v32 offset:42432
	ds_write_b16_d16_hi v2, v32 offset:42704
	ds_write_b16 v1, v33 offset:42976
	ds_write_b16_d16_hi v2, v33 offset:43248
	v_and_or_b32 v1, v59, s0, v0
	v_add_u32_e32 v6, s20, v56
	s_movk_i32 s0, 0x110
	v_mad_u64_u32 v[54:55], s[0:1], v1, s0, v[6:7]
	s_waitcnt lgkmcnt(0)
	s_barrier
	ds_read_b128 v[2:5], v54
	ds_read_b128 v[38:41], v54 offset:64
	ds_read_b128 v[34:37], v54 offset:4352
	v_mul_u32_u24_e32 v1, 0x88, v0
	v_lshl_add_u32 v1, v1, 1, v6
	ds_read_b128 v[6:9], v1 offset:34816
	ds_read_b128 v[14:17], v1 offset:39168
	ds_read_b128 v[22:25], v1 offset:43520
	ds_read_b128 v[46:49], v1 offset:43584
	ds_read_b128 v[30:33], v1 offset:47872
	ds_read_b128 v[50:53], v1 offset:47936
	s_waitcnt lgkmcnt(5)
	v_mfma_f32_16x16x32_bf16 v[10:13], v[2:5], v[6:9], 0
	ds_read_b128 v[42:45], v1 offset:39232
	v_lshlrev_b32_e32 v0, 8, v0
	s_waitcnt lgkmcnt(5)
	v_mfma_f32_16x16x32_bf16 v[18:21], v[2:5], v[14:17], 0
	s_waitcnt lgkmcnt(4)
	v_mfma_f32_16x16x32_bf16 v[26:29], v[2:5], v[22:25], 0
	s_waitcnt lgkmcnt(2)
	v_mfma_f32_16x16x32_bf16 v[2:5], v[2:5], v[30:33], 0
	v_mfma_f32_16x16x32_bf16 v[6:9], v[34:37], v[6:9], 0
	v_mfma_f32_16x16x32_bf16 v[14:17], v[34:37], v[14:17], 0
	v_mfma_f32_16x16x32_bf16 v[22:25], v[34:37], v[22:25], 0
	v_mfma_f32_16x16x32_bf16 v[30:33], v[34:37], v[30:33], 0
	ds_read_b128 v[34:37], v1 offset:34880
	s_waitcnt lgkmcnt(0)
	v_mfma_f32_16x16x32_bf16 v[10:13], v[38:41], v[34:37], v[10:13]
	v_mfma_f32_16x16x32_bf16 v[18:21], v[38:41], v[42:45], v[18:21]
	v_mfma_f32_16x16x32_bf16 v[26:29], v[38:41], v[46:49], v[26:29]
	v_mfma_f32_16x16x32_bf16 v[2:5], v[38:41], v[50:53], v[2:5]
	ds_read_b128 v[38:41], v54 offset:4416
	s_waitcnt lgkmcnt(0)
	v_mfma_f32_16x16x32_bf16 v[6:9], v[38:41], v[34:37], v[6:9]
	ds_read_b128 v[34:37], v54 offset:128
	v_mfma_f32_16x16x32_bf16 v[14:17], v[38:41], v[42:45], v[14:17]
	ds_read_b128 v[42:45], v1 offset:39296
	v_mfma_f32_16x16x32_bf16 v[22:25], v[38:41], v[46:49], v[22:25]
	ds_read_b128 v[46:49], v1 offset:43648
	v_mfma_f32_16x16x32_bf16 v[30:33], v[38:41], v[50:53], v[30:33]
	ds_read_b128 v[38:41], v1 offset:34944
	ds_read_b128 v[50:53], v1 offset:48000
	s_waitcnt lgkmcnt(1)
	v_mfma_f32_16x16x32_bf16 v[10:13], v[34:37], v[38:41], v[10:13]
	v_mfma_f32_16x16x32_bf16 v[18:21], v[34:37], v[42:45], v[18:21]
	v_mfma_f32_16x16x32_bf16 v[26:29], v[34:37], v[46:49], v[26:29]
	s_waitcnt lgkmcnt(0)
	v_mfma_f32_16x16x32_bf16 v[2:5], v[34:37], v[50:53], v[2:5]
	ds_read_b128 v[34:37], v54 offset:4480
	s_waitcnt lgkmcnt(0)
	v_mfma_f32_16x16x32_bf16 v[6:9], v[34:37], v[38:41], v[6:9]
	ds_read_b128 v[38:41], v54 offset:192
	v_mfma_f32_16x16x32_bf16 v[14:17], v[34:37], v[42:45], v[14:17]
	ds_read_b128 v[42:45], v1 offset:39360
	v_mfma_f32_16x16x32_bf16 v[22:25], v[34:37], v[46:49], v[22:25]
	ds_read_b128 v[46:49], v1 offset:43712
	v_mfma_f32_16x16x32_bf16 v[30:33], v[34:37], v[50:53], v[30:33]
	ds_read_b128 v[34:37], v1 offset:35008
	ds_read_b128 v[50:53], v1 offset:48064
	v_and_b32_e32 v1, 32, v59
	s_waitcnt lgkmcnt(1)
	v_mfma_f32_16x16x32_bf16 v[10:13], v[38:41], v[34:37], v[10:13]
	v_lshl_or_b32 v1, v1, 2, v56
	v_mfma_f32_16x16x32_bf16 v[18:21], v[38:41], v[42:45], v[18:21]
	v_mfma_f32_16x16x32_bf16 v[26:29], v[38:41], v[46:49], v[26:29]
	s_waitcnt lgkmcnt(0)
	v_mfma_f32_16x16x32_bf16 v[2:5], v[38:41], v[50:53], v[2:5]
	ds_read_b128 v[38:41], v54 offset:4544
	s_waitcnt lgkmcnt(0)
	v_mfma_f32_16x16x32_bf16 v[6:9], v[38:41], v[34:37], v[6:9]
	v_ashrrev_i32_e32 v34, 7, v58
	v_ashrrev_i32_e32 v35, 31, v34
	v_lshlrev_b64 v[34:35], 14, v[34:35]
	v_or3_b32 v34, v34, v0, v1
	v_lshl_add_u64 v[0:1], s[30:31], 0, v[34:35]
	global_store_dwordx4 v[0:1], v[10:13], off
	v_mfma_f32_16x16x32_bf16 v[14:17], v[38:41], v[42:45], v[14:17]
	s_nop 0
	v_add_co_u32_e32 v10, vcc, 0x1000, v0
	v_mfma_f32_16x16x32_bf16 v[22:25], v[38:41], v[46:49], v[22:25]
	s_nop 0
	v_addc_co_u32_e32 v11, vcc, 0, v1, vcc
	v_add_co_u32_e32 v12, vcc, 0x2000, v0
	global_store_dwordx4 v[10:11], v[18:21], off
	s_nop 0
	v_addc_co_u32_e32 v13, vcc, 0, v1, vcc
	v_add_co_u32_e32 v18, vcc, 0x3000, v0
	v_mfma_f32_16x16x32_bf16 v[30:33], v[38:41], v[50:53], v[30:33]
	s_nop 0
	v_addc_co_u32_e32 v19, vcc, 0, v1, vcc
	global_store_dwordx4 v[12:13], v[26:29], off
	global_store_dwordx4 v[18:19], v[2:5], off
	global_store_dwordx4 v[0:1], v[6:9], off offset:64
	global_store_dwordx4 v[10:11], v[14:17], off offset:64
	global_store_dwordx4 v[12:13], v[22:25], off offset:64
	s_nop 0
	global_store_dwordx4 v[18:19], v[30:33], off offset:64
	s_barrier
